# v4 plus: mLSTM inter-chunk LDS reads pipelined, P2 independent loads overlapped, late weight copies shared 4:1 between GLA and mLSTM workgroups
# speedup vs baseline: 1.0044x; 1.0044x over previous
; #define GAS __attribute__((address_space(1)))
; #define LAS __attribute__((address_space(3)))
; __device__ __forceinline__ void prep_unit(LAS unsigned char* lds, const MixBufs& B, int b, int ch, int tid) {
;     ...
;     const size_t t0 = (size_t)b * T + (size_t)ch * CH;
;     const int cq = tid & 63;
;     const int gch = tid & 127, strip = tid >> 7;
;     u32x2 xr[19];
;     LAS float* AL = (LAS float*)lds;
;     LAS float* CUM = (LAS float*)(lds + 4096);
;     LAS float* TOT = (LAS float*)(lds + 4096 + 65536);
; #pragma unroll
;     for (int i0 = 0; i0 < 1024; i0 += 512) { const int i = i0 + tid, r = i >> 4, j = i & 15; AL[i] = __uint_as_float((unsigned)B.PROJ[(t0 + r) * NPROJ + PC_AL + j] << 16); }
;     {
;         f32x4 wa[16];
; #pragma unroll
;         for (int j = 0; j < 16; ++j) wa[j] = *(const GAS f32x4*)(B.w_a_up + j * 256 + 4 * cq);
;         const f32x4 bias = *(const GAS f32x4*)(B.b_a_up + 4 * cq);
;         __syncthreads();
.LBB0_293:
	s_ashr_i32 s14, s26, 5
	s_and_b32 s27, s26, 31
	v_mov_b32_e32 v99, v0
	s_ashr_i32 s15, s14, 31
	s_lshl_b64 s[16:17], s[14:15], 11
	s_lshl_b32 s2, s27, 6
	v_ashrrev_i32_e32 v4, 4, v99
	s_or_b32 s16, s16, s2
	v_ashrrev_i32_e32 v5, 31, v4
	v_lshl_add_u64 v[4:5], s[16:17], 0, v[4:5]
	v_and_b32_e32 v100, 15, v99
	v_mad_u64_u32 v[6:7], s[2:3], v4, s11, v[76:77]
	v_mad_i32_i24 v7, v5, s11, v7
	v_lshlrev_b32_e32 v2, 1, v100
	v_lshl_add_u64 v[4:5], v[6:7], 0, v[2:3]
	v_add_co_u32_e32 v4, vcc, s20, v4
	v_and_b32_e32 v97, 63, v99
	s_nop 0
	v_addc_co_u32_e32 v5, vcc, 0, v5, vcc
	global_load_ushort v126, v[4:5], off offset:1024
	v_lshlrev_b32_e32 v78, 4, v97
	v_mov_b32_e32 v79, v3
	v_lshl_add_u64 v[52:53], s[58:59], 0, v[78:79]
	v_lshl_add_u32 v98, v99, 2, 0
	v_readfirstlane_b32 s19, v99
	s_ashr_i32 s18, s19, 6
	s_lshl_b32 s28, s18, 13
	v_lshlrev_b32_e32 v80, 2, v97
	s_mov_b32 s5, 0
	v_mov_b32_e32 v72, 0
	v_mov_b32_e32 v73, v3
	v_mov_b32_e32 v74, v3
	v_mov_b32_e32 v75, v3
	s_nop 0
	s_nop 0
	v_add_u32_e32 v4, 0x200, v99
	v_ashrrev_i32_e32 v4, 4, v4
	v_ashrrev_i32_e32 v5, 31, v4
	v_lshl_add_u64 v[4:5], s[16:17], 0, v[4:5]
	v_mad_u64_u32 v[6:7], s[2:3], v4, s11, v[76:77]
	v_mad_i32_i24 v7, v5, s11, v7
	v_lshl_add_u64 v[4:5], v[6:7], 0, v[2:3]
	v_add_co_u32_e32 v4, vcc, s20, v4
	s_movk_i32 s2, 0x3000
	s_nop 0
	v_addc_co_u32_e32 v5, vcc, 0, v5, vcc
	global_load_ushort v127, v[4:5], off offset:1024
	v_add_co_u32_e32 v32, vcc, s21, v52
	s_nop 0
	s_nop 0
	v_addc_co_u32_e32 v33, vcc, 0, v53, vcc
	v_add_co_u32_e32 v48, vcc, s20, v52
	s_nop 0
	s_nop 0
	v_addc_co_u32_e32 v49, vcc, 0, v53, vcc
	global_load_dwordx4 v[4:7], v78, s[58:59]
	global_load_dwordx4 v[8:11], v78, s[58:59] offset:1024
	global_load_dwordx4 v[12:15], v78, s[58:59] offset:2048
	global_load_dwordx4 v[16:19], v78, s[58:59] offset:3072
	global_load_dwordx4 v[20:23], v[48:49], off offset:-4096
	global_load_dwordx4 v[24:27], v[32:33], off offset:1024
	global_load_dwordx4 v[28:31], v[32:33], off offset:2048
	s_nop 0
	global_load_dwordx4 v[32:35], v[32:33], off offset:3072
	s_nop 0
	global_load_dwordx4 v[36:39], v[48:49], off
	global_load_dwordx4 v[40:43], v[48:49], off offset:1024
	global_load_dwordx4 v[44:47], v[48:49], off offset:2048
	s_nop 0
	global_load_dwordx4 v[48:51], v[48:49], off offset:3072
	v_add_co_u32_e32 v64, vcc, s2, v52
	s_add_i32 s2, s28, 0
	s_nop 0
	v_addc_co_u32_e32 v65, vcc, 0, v53, vcc
	global_load_dwordx4 v[52:55], v[64:65], off
	global_load_dwordx4 v[56:59], v[64:65], off offset:1024
	global_load_dwordx4 v[60:63], v[64:65], off offset:2048
	s_nop 0
	global_load_dwordx4 v[64:67], v[64:65], off offset:3072
	s_addk_i32 s2, 0x1000
	global_load_dwordx4 v[68:71], v78, s[60:61]
	v_add_u32_e32 v2, s2, v78
	s_lshl_b32 s2, s18, 9
	s_add_i32 s4, s2, 0
	s_waitcnt vmcnt(17)
	v_lshlrev_b32_e32 v126, 16, v126
	v_lshlrev_b32_e32 v127, 16, v127
	ds_write2st64_b32 v98, v126, v127 offset1:8
	s_waitcnt lgkmcnt(0)
	s_barrier

; #define GAS __attribute__((address_space(1)))
; #define LAS __attribute__((address_space(3)))
; __device__ __forceinline__ void prep_unit(LAS unsigned char* lds, const MixBufs& B, int b, int ch, int tid) {
;     ...
;       for (int s = 0; s < 19; ++s) { const int back = 3 - s; const size_t row = (s < 3 && ts0 < back) ? t0 : (t0 + 16 * strip + s - 3);
;           xr[s] = *(const GAS u32x2*)(B.PROJ + row * NPROJ + PC_XM + 4 * gch); if (s < 3 && ts0 < back) xr[s] = (u32x2){0u, 0u}; } }
;     {
;         f32x4 off = (f32x4){0.f, 0.f, 0.f, 0.f};
;         for (int ww = 0; ww < w; ++ww) off += *(const LAS f32x4*)(TOT + ww * 256 + 4 * cq);
; #pragma unroll
;         for (int s = 0; s < 8; ++s) { const int r = 8 * w + s;
;             const f32x4 cum = *(const LAS f32x4*)(CUM + r * 256 + 4 * cq) + off;
;             f32x4 ep;
; #pragma unroll
;             for (int e = 0; e < 4; ++e) ep[e] = fexp(cum[e]);
;             *(GAS u32x2*)(B.Eg + (t0 + r) * 256 + 4 * cq) = f32_to_bf4(ep);
;             if (r == CH - 1) *(GAS f32x4*)(B.dlast + ((size_t)b * NCH + ch) * 256 + 4 * cq) = ep; }
;     }
;     __syncthreads();
;     LAS unsigned char* XA = lds;
;     {
;         f32x4 cw[4], wv[4];
; #pragma unroll
;         for (int i = 0; i < 4; ++i) { cw[i] = *(const GAS f32x4*)(B.conv_w + i * 512 + 4 * gch); wv[i] = *(const GAS f32x4*)(B.w_v + (gch * 4 + i) * 4); }
;         const f32x4 cb = *(const GAS f32x4*)(B.conv_b + 4 * gch);
;         f32x4 x3 = bf4_to_f32(xr[0]), x2 = bf4_to_f32(xr[1]), x1 = bf4_to_f32(xr[2]);
; #pragma unroll
;         for (int s = 0; s < 16; ++s) { const int row = 16 * strip + s;
;             const f32x4 x0 = bf4_to_f32(xr[s + 3]);
;             f32x4 cv = cb + cw[0] * x3 + cw[1] * x2 + cw[2] * x1 + cw[3] * x0, xc;
; #pragma unroll
;             for (int e = 0; e < 4; ++e) xc[e] = cv[e] * fsigmoid(cv[e]);
;             const int sw = row & 7, within = (gch & 1) * 8;
;             *(LAS u32x2*)(XA + row * 2048 + ((((gch >> 1)) ^ sw) << 4) + within) = f32_to_bf4(xc);
;             *(LAS u32x2*)(XA + row * 2048 + (((64 + (gch >> 1)) ^ sw) << 4) + within) = xr[s + 3];
;             const f32x4 v = wv[0] * x0[0] + wv[1] * x0[1] + wv[2] * x0[2] + wv[3] * x0[3];
;             *(GAS u32x2*)(B.xcm + (t0 + row) * 512 + 4 * gch) = f32_to_bf4(xc); *(GAS u32x2*)(B.vm + (t0 + row) * 512 + 4 * gch) = f32_to_bf4(v);
;             x3 = x2; x2 = x1; x1 = x0; }
.LBB0_306:
	v_lshlrev_b32_e32 v2, 2, v59
	v_lshl_add_u64 v[28:29], s[64:65], 0, v[2:3]
	v_readlane_b32 s68, v241, 2
	v_add_co_u32_e32 v32, vcc, s21, v28
	v_lshlrev_b32_e32 v16, 6, v14
	v_readlane_b32 s72, v241, 6
	v_readlane_b32 s73, v241, 7
	v_addc_co_u32_e32 v33, vcc, 0, v29, vcc
	s_waitcnt vmcnt(26)
	v_cndmask_b32_e64 v92, v13, 0, s[2:3]
	v_cndmask_b32_e64 v80, v12, 0, s[2:3]
	s_waitcnt vmcnt(25)
	v_cndmask_b32_e64 v93, v11, 0, s[4:5]
	v_cndmask_b32_e64 v81, v10, 0, s[4:5]
	s_waitcnt vmcnt(24)
	v_cndmask_b32_e64 v101, v9, 0, s[6:7]
	v_cndmask_b32_e64 v87, v8, 0, s[6:7]
	s_barrier
	global_load_dwordx4 v[20:23], v2, s[64:65]
	global_load_dwordx4 v[4:7], v16, s[72:73] offset:48
	global_load_dwordx4 v[8:11], v16, s[72:73] offset:32
	global_load_dwordx4 v[12:15], v16, s[72:73]
	s_nop 0
	global_load_dwordx4 v[16:19], v16, s[72:73] offset:16
	s_nop 0
	global_load_dwordx4 v[24:27], v2, s[64:65] offset:2048
	global_load_dwordx4 v[28:31], v[32:33], off
	s_nop 0
	global_load_dwordx4 v[32:35], v[32:33], off offset:2048
	s_nop 0
	global_load_dwordx4 v[36:39], v2, s[66:67]
	v_lshlrev_b32_e32 v84, 16, v80
	v_and_b32_e32 v85, 0xffff0000, v80
	v_lshlrev_b32_e32 v90, 16, v81
	v_and_b32_e32 v91, 0xffff0000, v81
	v_lshlrev_b32_e32 v86, 16, v87
	v_and_b32_e32 v87, 0xffff0000, v87
	s_waitcnt vmcnt(32)
	v_and_b32_e32 v103, 0xffff0000, v82
	v_lshlrev_b32_e32 v80, 16, v82
	v_mov_b32_e32 v81, v103
	v_lshlrev_b32_e32 v2, 3, v99
	v_and_b32_e32 v41, 8, v2
	v_lshlrev_b32_e32 v106, 16, v92
	v_and_b32_e32 v107, 0xffff0000, v92
	v_lshlrev_b32_e32 v92, 16, v93
	v_and_b32_e32 v93, 0xffff0000, v93
	v_and_b32_e32 v109, 0xffff0000, v83
	v_and_b32_e32 v102, 16, v82
	v_and_b32_e32 v108, 16, v83
	v_readlane_b32 s36, v241, 18
	v_lshlrev_b64 v[74:75], 10, v[74:75]
	v_readlane_b32 s50, v241, 32
	v_readlane_b32 s51, v241, 33
	s_movk_i32 s2, 0x50
	s_lshl_b32 s4, s18, 7
	s_ashr_i32 s5, s4, 31
	s_lshl_b32 s3, s18, 4
	v_readlane_b32 s76, v241, 10
	v_readlane_b32 s77, v241, 11
	v_readlane_b32 s69, v241, 3
	v_readlane_b32 s70, v241, 4
	v_readlane_b32 s71, v241, 5
	v_readlane_b32 s74, v241, 8
	v_readlane_b32 s75, v241, 9
	v_readlane_b32 s78, v241, 12
	v_readlane_b32 s79, v241, 13
	v_readlane_b32 s80, v241, 14
	v_readlane_b32 s81, v241, 15
	v_readlane_b32 s82, v241, 16
	v_readlane_b32 s83, v241, 17
	v_readlane_b32 s37, v241, 19
	v_readlane_b32 s38, v241, 20
	v_readlane_b32 s39, v241, 21
	v_readlane_b32 s40, v241, 22
	v_readlane_b32 s41, v241, 23
	v_readlane_b32 s42, v241, 24
	v_readlane_b32 s43, v241, 25
	v_readlane_b32 s44, v241, 26
	v_readlane_b32 s45, v241, 27
	v_readlane_b32 s46, v241, 28
	v_readlane_b32 s47, v241, 29
	v_readlane_b32 s48, v241, 30
	v_readlane_b32 s49, v241, 31
	s_waitcnt vmcnt(0)
	v_pk_fma_f32 v[84:85], v[20:21], v[84:85], v[36:37]
	s_nop 0
	v_pk_fma_f32 v[84:85], v[24:25], v[90:91], v[84:85]
	v_pk_fma_f32 v[106:107], v[22:23], v[106:107], v[38:39]
	v_pk_fma_f32 v[84:85], v[28:29], v[86:87], v[84:85]
	v_pk_fma_f32 v[106:107], v[26:27], v[92:93], v[106:107]
	v_pk_fma_f32 v[84:85], v[32:33], v[80:81], v[84:85]
	v_pk_fma_f32 v[90:91], v[20:21], v[90:91], v[36:37]
	v_mul_f32_e32 v2, 0xbfb8aa3b, v84
	v_exp_f32_e32 v2, v2
	v_pk_fma_f32 v[90:91], v[24:25], v[86:87], v[90:91]
	v_pk_fma_f32 v[92:93], v[22:23], v[92:93], v[38:39]
	v_pk_fma_f32 v[90:91], v[28:29], v[80:81], v[90:91]
	v_add_f32_e32 v2, 1.0, v2
	v_rcp_f32_e32 v88, v2
	v_mul_f32_e32 v2, 0xbfb8aa3b, v85
	v_exp_f32_e32 v2, v2
	s_nop 0
	v_add_f32_e32 v2, 1.0, v2
	v_rcp_f32_e32 v89, v2
	s_nop 0
	v_pk_mul_f32 v[104:105], v[84:85], v[88:89]
	v_lshlrev_b32_e32 v88, 16, v101
	v_and_b32_e32 v89, 0xffff0000, v101
	v_lshlrev_b32_e32 v84, 16, v83
	v_mov_b32_e32 v85, v109
	v_pk_fma_f32 v[106:107], v[30:31], v[88:89], v[106:107]
	v_and_b32_e32 v101, 0x3f0, v58
	v_pk_fma_f32 v[106:107], v[34:35], v[84:85], v[106:107]
	v_cvt_pk_bf16_f32 v104, v104, v105
	v_mul_f32_e32 v2, 0xbfb8aa3b, v106
	v_exp_f32_e32 v2, v2
	v_pk_fma_f32 v[92:93], v[26:27], v[88:89], v[92:93]
	v_pk_fma_f32 v[88:89], v[22:23], v[88:89], v[38:39]
	v_pk_fma_f32 v[92:93], v[30:31], v[84:85], v[92:93]
	v_add_f32_e32 v2, 1.0, v2
	v_rcp_f32_e32 v110, v2
	v_mul_f32_e32 v2, 0xbfb8aa3b, v107
	v_exp_f32_e32 v2, v2
	v_pk_fma_f32 v[88:89], v[26:27], v[84:85], v[88:89]
	v_add_f32_e32 v2, 1.0, v2
	v_rcp_f32_e32 v111, v2
	v_lshl_add_u32 v2, v40, 11, 0
	v_add3_u32 v2, v2, v101, v41
	v_pk_mul_f32 v[106:107], v[106:107], v[110:111]
	s_nop 0
	v_cvt_pk_bf16_f32 v105, v106, v107
	ds_write2st64_b64 v2, v[104:105], v[82:83] offset1:2
	v_pk_mul_f32 v[82:83], v[102:103], v[18:19] op_sel:[1,0]
	v_pk_mul_f32 v[102:103], v[102:103], v[16:17] op_sel:[1,0]
	v_pk_fma_f32 v[82:83], v[80:81], v[14:15], v[82:83] op_sel_hi:[0,1,1]
	v_pk_fma_f32 v[102:103], v[80:81], v[12:13], v[102:103] op_sel_hi:[0,1,1]
	v_pk_fma_f32 v[82:83], v[84:85], v[10:11], v[82:83] op_sel_hi:[0,1,1]
	v_pk_fma_f32 v[102:103], v[84:85], v[8:9], v[102:103] op_sel_hi:[0,1,1]
	v_pk_fma_f32 v[82:83], v[108:109], v[6:7], v[82:83] op_sel:[1,0,0]
	v_pk_fma_f32 v[102:103], v[108:109], v[4:5], v[102:103] op_sel:[1,0,0]
	v_lshl_add_u64 v[106:107], s[50:51], 0, v[74:75]
	v_lshlrev_b32_e32 v2, 1, v59
	v_lshl_add_u64 v[74:75], s[0:1], 0, v[74:75]
	v_cvt_pk_bf16_f32 v102, v102, v103
	v_cvt_pk_bf16_f32 v103, v82, v83
	v_lshl_add_u64 v[74:75], v[74:75], 0, v[2:3]
	v_and_b32_e32 v83, 0xffff0000, v72
	global_store_dwordx2 v[74:75], v[102:103], off
	v_lshlrev_b32_e32 v74, 16, v72
	v_mov_b32_e32 v75, v83
	v_pk_fma_f32 v[90:91], v[32:33], v[74:75], v[90:91]
	v_lshl_add_u64 v[106:107], v[106:107], 0, v[2:3]
	v_mul_f32_e32 v59, 0xbfb8aa3b, v90
	v_exp_f32_e32 v59, v59
	global_store_dwordx2 v[106:107], v[104:105], off
	v_and_b32_e32 v105, 0xffff0000, v73
; #define GAS __attribute__((address_space(1)))
; #define LAS __attribute__((address_space(3)))
; __device__ __forceinline__ float fsigmoid(float x) { return __builtin_amdgcn_rcpf(1.f + __builtin_amdgcn_exp2f(-LOG2E * x)); }
; __device__ __forceinline__ f32x4 bf4_to_f32(u32x2 w) { return (f32x4){bflo(w.x), bfhi(w.x), bflo(w.y), bfhi(w.y)}; }
; __device__ __forceinline__ u32x2 f32_to_bf4(f32x4 v) { u32x2 w; w.x = cvtpk(v[0], v[1]); w.y = cvtpk(v[2], v[3]); return w; }
; __device__ __forceinline__ void prep_unit(LAS unsigned char* lds, const MixBufs& B, int b, int ch, int tid) {
;     ...
;         for (int s = 0; s < 16; ++s) { const int row = 16 * strip + s;
;             const f32x4 x0 = bf4_to_f32(xr[s + 3]);
;             f32x4 cv = cb + cw[0] * x3 + cw[1] * x2 + cw[2] * x1 + cw[3] * x0, xc;
; #pragma unroll
;             for (int e = 0; e < 4; ++e) xc[e] = cv[e] * fsigmoid(cv[e]);
;             const int sw = row & 7, within = (gch & 1) * 8;
;             *(LAS u32x2*)(XA + row * 2048 + ((((gch >> 1)) ^ sw) << 4) + within) = f32_to_bf4(xc);
;             *(LAS u32x2*)(XA + row * 2048 + (((64 + (gch >> 1)) ^ sw) << 4) + within) = xr[s + 3];
;             const f32x4 v = wv[0] * x0[0] + wv[1] * x0[1] + wv[2] * x0[2] + wv[3] * x0[3];
;             *(GAS u32x2*)(B.xcm + (t0 + row) * 512 + 4 * gch) = f32_to_bf4(xc); *(GAS u32x2*)(B.vm + (t0 + row) * 512 + 4 * gch) = f32_to_bf4(v);
;             x3 = x2; x2 = x1; x1 = x0; }
	v_and_b32_e32 v82, 16, v72
	v_add_f32_e32 v59, 1.0, v59
	v_rcp_f32_e32 v102, v59
	v_mul_f32_e32 v59, 0xbfb8aa3b, v91
	v_exp_f32_e32 v59, v59
	v_and_b32_e32 v104, 16, v73
	v_pk_fma_f32 v[84:85], v[22:23], v[84:85], v[38:39]
	v_add_f32_e32 v59, 1.0, v59
	v_rcp_f32_e32 v103, v59
	s_nop 0
	v_pk_mul_f32 v[102:103], v[90:91], v[102:103]
	v_lshlrev_b32_e32 v90, 16, v73
	v_mov_b32_e32 v91, v105
	v_pk_fma_f32 v[92:93], v[34:35], v[90:91], v[92:93]
	v_cvt_pk_bf16_f32 v108, v102, v103
	v_mul_f32_e32 v59, 0xbfb8aa3b, v92
	v_exp_f32_e32 v59, v59
	v_bitop3_b32 v102, v58, 16, v94 bitop3:0x6c
	v_pk_fma_f32 v[88:89], v[30:31], v[90:91], v[88:89]
	v_pk_fma_f32 v[84:85], v[26:27], v[90:91], v[84:85]
	v_add_f32_e32 v59, 1.0, v59
	v_rcp_f32_e32 v106, v59
	v_mul_f32_e32 v59, 0xbfb8aa3b, v93
	v_exp_f32_e32 v59, v59
	s_nop 0
	v_add_f32_e32 v59, 1.0, v59
	v_rcp_f32_e32 v107, v59
	s_nop 0
	v_pk_mul_f32 v[92:93], v[92:93], v[106:107]
	v_or_b32_e32 v106, 1, v40
	v_lshl_add_u32 v59, v106, 11, 0
	v_cvt_pk_bf16_f32 v109, v92, v93
	v_add3_u32 v59, v59, v102, v41
	ds_write2st64_b64 v59, v[108:109], v[72:73] offset1:2
	v_pk_mul_f32 v[72:73], v[82:83], v[18:19] op_sel:[1,0]
	v_pk_mul_f32 v[82:83], v[82:83], v[16:17] op_sel:[1,0]
	v_pk_fma_f32 v[72:73], v[74:75], v[14:15], v[72:73] op_sel_hi:[0,1,1]
	v_pk_fma_f32 v[82:83], v[74:75], v[12:13], v[82:83] op_sel_hi:[0,1,1]
	v_ashrrev_i32_e32 v107, 31, v106
	v_pk_fma_f32 v[72:73], v[90:91], v[10:11], v[72:73] op_sel_hi:[0,1,1]
	v_pk_fma_f32 v[82:83], v[90:91], v[8:9], v[82:83] op_sel_hi:[0,1,1]
	v_lshl_add_u64 v[92:93], s[16:17], 0, v[106:107]
	v_pk_fma_f32 v[72:73], v[104:105], v[6:7], v[72:73] op_sel:[1,0,0]
	v_pk_fma_f32 v[82:83], v[104:105], v[4:5], v[82:83] op_sel:[1,0,0]
	v_lshlrev_b64 v[92:93], 10, v[92:93]
	v_cvt_pk_bf16_f32 v82, v82, v83
	v_cvt_pk_bf16_f32 v83, v72, v73
	v_lshl_add_u64 v[72:73], s[0:1], 0, v[92:93]
	v_lshl_add_u64 v[72:73], v[72:73], 0, v[2:3]
	global_store_dwordx2 v[72:73], v[82:83], off
	v_pk_fma_f32 v[82:83], v[20:21], v[86:87], v[36:37]
	v_and_b32_e32 v73, 0xffff0000, v70
	v_pk_fma_f32 v[82:83], v[24:25], v[80:81], v[82:83]
	v_lshl_add_u64 v[104:105], s[50:51], 0, v[92:93]
	v_lshlrev_b32_e32 v92, 16, v70
	v_mov_b32_e32 v93, v73
	v_pk_fma_f32 v[82:83], v[28:29], v[74:75], v[82:83]
	v_lshl_add_u64 v[104:105], v[104:105], 0, v[2:3]
	v_pk_fma_f32 v[82:83], v[32:33], v[92:93], v[82:83]
	global_store_dwordx2 v[104:105], v[108:109], off
	v_mul_f32_e32 v59, 0xbfb8aa3b, v82
	v_exp_f32_e32 v59, v59
	v_and_b32_e32 v105, 0xffff0000, v71
	v_and_b32_e32 v72, 16, v70
	v_and_b32_e32 v104, 16, v71
	v_add_f32_e32 v59, 1.0, v59
	v_rcp_f32_e32 v86, v59
	v_mul_f32_e32 v59, 0xbfb8aa3b, v83
	v_exp_f32_e32 v59, v59
	v_pk_fma_f32 v[90:91], v[22:23], v[90:91], v[38:39]
	v_add_f32_e32 v59, 1.0, v59
	v_rcp_f32_e32 v87, v59
	s_nop 0
	v_pk_mul_f32 v[82:83], v[82:83], v[86:87]
	v_lshlrev_b32_e32 v86, 16, v71
	v_mov_b32_e32 v87, v105
	v_pk_fma_f32 v[88:89], v[34:35], v[86:87], v[88:89]
	v_cvt_pk_bf16_f32 v82, v82, v83
	v_mul_f32_e32 v59, 0xbfb8aa3b, v88
	v_exp_f32_e32 v59, v59
	v_pk_fma_f32 v[84:85], v[30:31], v[86:87], v[84:85]
	v_pk_fma_f32 v[90:91], v[26:27], v[86:87], v[90:91]
	v_add_f32_e32 v59, 1.0, v59
	v_rcp_f32_e32 v106, v59
	v_mul_f32_e32 v59, 0xbfb8aa3b, v89
	v_exp_f32_e32 v59, v59
	s_nop 0
	v_add_f32_e32 v59, 1.0, v59
	v_rcp_f32_e32 v107, v59
	s_nop 0
	v_pk_mul_f32 v[88:89], v[88:89], v[106:107]
	v_or_b32_e32 v106, 2, v40
	v_cvt_pk_bf16_f32 v83, v88, v89
	v_lshl_add_u32 v59, v106, 11, 0
	v_bitop3_b32 v88, v58, 32, v94 bitop3:0x6c
	v_add3_u32 v59, v59, v88, v41
	ds_write2st64_b64 v59, v[82:83], v[70:71] offset1:2
	v_pk_mul_f32 v[70:71], v[72:73], v[18:19] op_sel:[1,0]
	v_pk_mul_f32 v[72:73], v[72:73], v[16:17] op_sel:[1,0]
	v_pk_fma_f32 v[70:71], v[92:93], v[14:15], v[70:71] op_sel_hi:[0,1,1]
	v_pk_fma_f32 v[72:73], v[92:93], v[12:13], v[72:73] op_sel_hi:[0,1,1]
	v_pk_fma_f32 v[70:71], v[86:87], v[10:11], v[70:71] op_sel_hi:[0,1,1]
	v_pk_fma_f32 v[72:73], v[86:87], v[8:9], v[72:73] op_sel_hi:[0,1,1]
	v_ashrrev_i32_e32 v107, 31, v106
	v_pk_fma_f32 v[70:71], v[104:105], v[6:7], v[70:71] op_sel:[1,0,0]
	v_pk_fma_f32 v[72:73], v[104:105], v[4:5], v[72:73] op_sel:[1,0,0]
	v_lshl_add_u64 v[104:105], s[16:17], 0, v[106:107]
	v_lshlrev_b64 v[104:105], 10, v[104:105]
	v_cvt_pk_bf16_f32 v72, v72, v73
	v_cvt_pk_bf16_f32 v73, v70, v71
	v_lshl_add_u64 v[70:71], s[0:1], 0, v[104:105]
	v_lshl_add_u64 v[70:71], v[70:71], 0, v[2:3]
	v_lshl_add_u64 v[106:107], s[50:51], 0, v[104:105]
	global_store_dwordx2 v[70:71], v[72:73], off
	v_pk_fma_f32 v[72:73], v[20:21], v[80:81], v[36:37]
	v_lshl_add_u64 v[106:107], v[106:107], 0, v[2:3]
	v_and_b32_e32 v71, 0xffff0000, v68
	v_pk_fma_f32 v[72:73], v[24:25], v[74:75], v[72:73]
	global_store_dwordx2 v[106:107], v[82:83], off
	v_lshlrev_b32_e32 v82, 16, v68
	v_mov_b32_e32 v83, v71
	v_pk_fma_f32 v[72:73], v[28:29], v[92:93], v[72:73]
	v_and_b32_e32 v105, 0xffff0000, v69
	v_pk_fma_f32 v[72:73], v[32:33], v[82:83], v[72:73]
	v_and_b32_e32 v70, 16, v68
	v_mul_f32_e32 v59, 0xbfb8aa3b, v72
	v_exp_f32_e32 v59, v59
	v_and_b32_e32 v104, 16, v69
	v_pk_fma_f32 v[86:87], v[22:23], v[86:87], v[38:39]
	v_add_f32_e32 v59, 1.0, v59
	v_rcp_f32_e32 v80, v59
	v_mul_f32_e32 v59, 0xbfb8aa3b, v73
	v_exp_f32_e32 v59, v59
	s_nop 0
	v_add_f32_e32 v59, 1.0, v59
	v_rcp_f32_e32 v81, v59
	s_nop 0
	v_pk_mul_f32 v[72:73], v[72:73], v[80:81]
	v_lshlrev_b32_e32 v80, 16, v69
	v_mov_b32_e32 v81, v105
	v_pk_fma_f32 v[84:85], v[34:35], v[80:81], v[84:85]
	v_cvt_pk_bf16_f32 v72, v72, v73
	v_mul_f32_e32 v59, 0xbfb8aa3b, v84
	v_exp_f32_e32 v59, v59
	v_pk_fma_f32 v[90:91], v[30:31], v[80:81], v[90:91]
	v_pk_fma_f32 v[86:87], v[26:27], v[80:81], v[86:87]
; #define GAS __attribute__((address_space(1)))
; #define LAS __attribute__((address_space(3)))
; __device__ __forceinline__ float fsigmoid(float x) { return __builtin_amdgcn_rcpf(1.f + __builtin_amdgcn_exp2f(-LOG2E * x)); }
; __device__ __forceinline__ f32x4 bf4_to_f32(u32x2 w) { return (f32x4){bflo(w.x), bfhi(w.x), bflo(w.y), bfhi(w.y)}; }
; __device__ __forceinline__ u32x2 f32_to_bf4(f32x4 v) { u32x2 w; w.x = cvtpk(v[0], v[1]); w.y = cvtpk(v[2], v[3]); return w; }
; __device__ __forceinline__ void prep_unit(LAS unsigned char* lds, const MixBufs& B, int b, int ch, int tid) {
;     ...
;         for (int s = 0; s < 16; ++s) { const int row = 16 * strip + s;
;             const f32x4 x0 = bf4_to_f32(xr[s + 3]);
;             f32x4 cv = cb + cw[0] * x3 + cw[1] * x2 + cw[2] * x1 + cw[3] * x0, xc;
; #pragma unroll
;             for (int e = 0; e < 4; ++e) xc[e] = cv[e] * fsigmoid(cv[e]);
;             const int sw = row & 7, within = (gch & 1) * 8;
;             *(LAS u32x2*)(XA + row * 2048 + ((((gch >> 1)) ^ sw) << 4) + within) = f32_to_bf4(xc);
;             *(LAS u32x2*)(XA + row * 2048 + (((64 + (gch >> 1)) ^ sw) << 4) + within) = xr[s + 3];
;             const f32x4 v = wv[0] * x0[0] + wv[1] * x0[1] + wv[2] * x0[2] + wv[3] * x0[3];
;             *(GAS u32x2*)(B.xcm + (t0 + row) * 512 + 4 * gch) = f32_to_bf4(xc); *(GAS u32x2*)(B.vm + (t0 + row) * 512 + 4 * gch) = f32_to_bf4(v);
;             x3 = x2; x2 = x1; x1 = x0; }
	v_add_f32_e32 v59, 1.0, v59
	v_rcp_f32_e32 v106, v59
	v_mul_f32_e32 v59, 0xbfb8aa3b, v85
	v_exp_f32_e32 v59, v59
	s_nop 0
	v_add_f32_e32 v59, 1.0, v59
	v_rcp_f32_e32 v107, v59
	s_nop 0
	v_pk_mul_f32 v[84:85], v[84:85], v[106:107]
	v_or_b32_e32 v106, 3, v40
	v_cvt_pk_bf16_f32 v73, v84, v85
	v_lshl_add_u32 v59, v106, 11, 0
	v_bitop3_b32 v84, v58, 48, v94 bitop3:0x6c
	v_add3_u32 v59, v59, v84, v41
	ds_write2st64_b64 v59, v[72:73], v[68:69] offset1:2
	v_pk_mul_f32 v[68:69], v[70:71], v[18:19] op_sel:[1,0]
	v_pk_mul_f32 v[70:71], v[70:71], v[16:17] op_sel:[1,0]
	v_pk_fma_f32 v[68:69], v[82:83], v[14:15], v[68:69] op_sel_hi:[0,1,1]
	v_pk_fma_f32 v[70:71], v[82:83], v[12:13], v[70:71] op_sel_hi:[0,1,1]
	v_pk_fma_f32 v[68:69], v[80:81], v[10:11], v[68:69] op_sel_hi:[0,1,1]
	v_pk_fma_f32 v[70:71], v[80:81], v[8:9], v[70:71] op_sel_hi:[0,1,1]
	v_ashrrev_i32_e32 v107, 31, v106
	v_pk_fma_f32 v[68:69], v[104:105], v[6:7], v[68:69] op_sel:[1,0,0]
	v_pk_fma_f32 v[70:71], v[104:105], v[4:5], v[70:71] op_sel:[1,0,0]
	v_lshl_add_u64 v[104:105], s[16:17], 0, v[106:107]
	v_lshlrev_b64 v[104:105], 10, v[104:105]
	v_lshl_add_u64 v[106:107], s[50:51], 0, v[104:105]
	v_lshl_add_u64 v[106:107], v[106:107], 0, v[2:3]
	v_cvt_pk_bf16_f32 v70, v70, v71
	v_cvt_pk_bf16_f32 v71, v68, v69
	v_lshl_add_u64 v[68:69], s[0:1], 0, v[104:105]
	global_store_dwordx2 v[106:107], v[72:73], off
	v_lshl_add_u64 v[68:69], v[68:69], 0, v[2:3]
	v_pk_fma_f32 v[72:73], v[20:21], v[74:75], v[36:37]
	global_store_dwordx2 v[68:69], v[70:71], off
	v_and_b32_e32 v69, 0xffff0000, v66
	v_pk_fma_f32 v[72:73], v[24:25], v[92:93], v[72:73]
	v_lshlrev_b32_e32 v70, 16, v66
	v_mov_b32_e32 v71, v69
	v_pk_fma_f32 v[72:73], v[28:29], v[82:83], v[72:73]
	v_and_b32_e32 v105, 0xffff0000, v67
	v_pk_fma_f32 v[72:73], v[32:33], v[70:71], v[72:73]
	v_bitop3_b32 v85, v58, 64, v94 bitop3:0x6c
	v_mul_f32_e32 v59, 0xbfb8aa3b, v72
	v_exp_f32_e32 v59, v59
	v_and_b32_e32 v68, 16, v66
	v_and_b32_e32 v104, 16, v67
	v_pk_fma_f32 v[80:81], v[22:23], v[80:81], v[38:39]
	v_add_f32_e32 v59, 1.0, v59
	v_rcp_f32_e32 v74, v59
	v_mul_f32_e32 v59, 0xbfb8aa3b, v73
	v_exp_f32_e32 v59, v59
	s_nop 0
	v_add_f32_e32 v59, 1.0, v59
	v_rcp_f32_e32 v75, v59
	s_nop 0
	v_pk_mul_f32 v[74:75], v[72:73], v[74:75]
	v_lshlrev_b32_e32 v72, 16, v67
	v_mov_b32_e32 v73, v105
	v_pk_fma_f32 v[90:91], v[34:35], v[72:73], v[90:91]
	v_cvt_pk_bf16_f32 v74, v74, v75
	v_mul_f32_e32 v59, 0xbfb8aa3b, v90
	v_exp_f32_e32 v59, v59
	v_pk_fma_f32 v[86:87], v[30:31], v[72:73], v[86:87]
	v_pk_fma_f32 v[80:81], v[26:27], v[72:73], v[80:81]
	v_add_f32_e32 v59, 1.0, v59
	v_rcp_f32_e32 v106, v59
	v_mul_f32_e32 v59, 0xbfb8aa3b, v91
	v_exp_f32_e32 v59, v59
	s_nop 0
	v_add_f32_e32 v59, 1.0, v59
	v_rcp_f32_e32 v107, v59
	s_nop 0
	v_pk_mul_f32 v[90:91], v[90:91], v[106:107]
	v_or_b32_e32 v106, 4, v40
	v_lshl_add_u32 v59, v106, 11, 0
	v_cvt_pk_bf16_f32 v75, v90, v91
	v_add3_u32 v59, v59, v85, v41
	ds_write2st64_b64 v59, v[74:75], v[66:67] offset1:2
	v_pk_mul_f32 v[66:67], v[68:69], v[18:19] op_sel:[1,0]
	v_pk_mul_f32 v[68:69], v[68:69], v[16:17] op_sel:[1,0]
	v_pk_fma_f32 v[66:67], v[70:71], v[14:15], v[66:67] op_sel_hi:[0,1,1]
	v_pk_fma_f32 v[68:69], v[70:71], v[12:13], v[68:69] op_sel_hi:[0,1,1]
	v_ashrrev_i32_e32 v107, 31, v106
	v_pk_fma_f32 v[66:67], v[72:73], v[10:11], v[66:67] op_sel_hi:[0,1,1]
	v_pk_fma_f32 v[68:69], v[72:73], v[8:9], v[68:69] op_sel_hi:[0,1,1]
	v_lshl_add_u64 v[90:91], s[16:17], 0, v[106:107]
	v_pk_fma_f32 v[66:67], v[104:105], v[6:7], v[66:67] op_sel:[1,0,0]
	v_pk_fma_f32 v[68:69], v[104:105], v[4:5], v[68:69] op_sel:[1,0,0]
	v_lshlrev_b64 v[90:91], 10, v[90:91]
	v_cvt_pk_bf16_f32 v68, v68, v69
	v_cvt_pk_bf16_f32 v69, v66, v67
	v_lshl_add_u64 v[66:67], s[0:1], 0, v[90:91]
	v_lshl_add_u64 v[104:105], s[50:51], 0, v[90:91]
	v_lshl_add_u64 v[66:67], v[66:67], 0, v[2:3]
	v_lshl_add_u64 v[104:105], v[104:105], 0, v[2:3]
	global_store_dwordx2 v[66:67], v[68:69], off
	v_pk_fma_f32 v[68:69], v[20:21], v[92:93], v[36:37]
	global_store_dwordx2 v[104:105], v[74:75], off
	v_and_b32_e32 v75, 0xffff0000, v64
	v_pk_fma_f32 v[68:69], v[24:25], v[82:83], v[68:69]
	v_lshlrev_b32_e32 v66, 16, v64
	v_mov_b32_e32 v67, v75
	v_pk_fma_f32 v[68:69], v[28:29], v[70:71], v[68:69]
	v_and_b32_e32 v93, 0xffff0000, v65
	v_pk_fma_f32 v[68:69], v[32:33], v[66:67], v[68:69]
	v_and_b32_e32 v74, 16, v64
	v_mul_f32_e32 v59, 0xbfb8aa3b, v68
	v_exp_f32_e32 v59, v59
	v_and_b32_e32 v92, 16, v65
	v_pk_fma_f32 v[72:73], v[22:23], v[72:73], v[38:39]
	v_add_f32_e32 v59, 1.0, v59
	v_rcp_f32_e32 v90, v59
	v_mul_f32_e32 v59, 0xbfb8aa3b, v69
	v_exp_f32_e32 v59, v59
	s_nop 0
	v_add_f32_e32 v59, 1.0, v59
	v_rcp_f32_e32 v91, v59
	s_nop 0
	v_pk_mul_f32 v[90:91], v[68:69], v[90:91]
	v_lshlrev_b32_e32 v68, 16, v65
	v_mov_b32_e32 v69, v93
	v_pk_fma_f32 v[86:87], v[34:35], v[68:69], v[86:87]
	v_cvt_pk_bf16_f32 v90, v90, v91
	v_mul_f32_e32 v59, 0xbfb8aa3b, v86
	v_exp_f32_e32 v59, v59
	v_pk_fma_f32 v[80:81], v[30:31], v[68:69], v[80:81]
	v_pk_fma_f32 v[72:73], v[26:27], v[68:69], v[72:73]
	v_add_f32_e32 v59, 1.0, v59
	v_rcp_f32_e32 v104, v59
	v_mul_f32_e32 v59, 0xbfb8aa3b, v87
	v_exp_f32_e32 v59, v59
	s_nop 0
	v_add_f32_e32 v59, 1.0, v59
	v_rcp_f32_e32 v105, v59
	s_nop 0
	v_pk_mul_f32 v[86:87], v[86:87], v[104:105]
	v_or_b32_e32 v104, 5, v40
	v_cvt_pk_bf16_f32 v91, v86, v87
	v_lshl_add_u32 v59, v104, 11, 0
	v_bitop3_b32 v86, v58, s2, v94 bitop3:0x6c
	v_add3_u32 v59, v59, v86, v41
	ds_write2st64_b64 v59, v[90:91], v[64:65] offset1:2
	v_pk_mul_f32 v[64:65], v[74:75], v[18:19] op_sel:[1,0]
	v_pk_mul_f32 v[74:75], v[74:75], v[16:17] op_sel:[1,0]
	v_pk_fma_f32 v[64:65], v[66:67], v[14:15], v[64:65] op_sel_hi:[0,1,1]
; #define GAS __attribute__((address_space(1)))
; #define LAS __attribute__((address_space(3)))
; __device__ __forceinline__ float fsigmoid(float x) { return __builtin_amdgcn_rcpf(1.f + __builtin_amdgcn_exp2f(-LOG2E * x)); }
; __device__ __forceinline__ f32x4 bf4_to_f32(u32x2 w) { return (f32x4){bflo(w.x), bfhi(w.x), bflo(w.y), bfhi(w.y)}; }
; __device__ __forceinline__ u32x2 f32_to_bf4(f32x4 v) { u32x2 w; w.x = cvtpk(v[0], v[1]); w.y = cvtpk(v[2], v[3]); return w; }
; __device__ __forceinline__ void prep_unit(LAS unsigned char* lds, const MixBufs& B, int b, int ch, int tid) {
;     ...
;         for (int s = 0; s < 16; ++s) { const int row = 16 * strip + s;
;             const f32x4 x0 = bf4_to_f32(xr[s + 3]);
;             f32x4 cv = cb + cw[0] * x3 + cw[1] * x2 + cw[2] * x1 + cw[3] * x0, xc;
; #pragma unroll
;             for (int e = 0; e < 4; ++e) xc[e] = cv[e] * fsigmoid(cv[e]);
;             const int sw = row & 7, within = (gch & 1) * 8;
;             *(LAS u32x2*)(XA + row * 2048 + ((((gch >> 1)) ^ sw) << 4) + within) = f32_to_bf4(xc);
;             *(LAS u32x2*)(XA + row * 2048 + (((64 + (gch >> 1)) ^ sw) << 4) + within) = xr[s + 3];
;             const f32x4 v = wv[0] * x0[0] + wv[1] * x0[1] + wv[2] * x0[2] + wv[3] * x0[3];
;             *(GAS u32x2*)(B.xcm + (t0 + row) * 512 + 4 * gch) = f32_to_bf4(xc); *(GAS u32x2*)(B.vm + (t0 + row) * 512 + 4 * gch) = f32_to_bf4(v);
;             x3 = x2; x2 = x1; x1 = x0; }
	v_pk_fma_f32 v[74:75], v[66:67], v[12:13], v[74:75] op_sel_hi:[0,1,1]
	v_pk_fma_f32 v[64:65], v[68:69], v[10:11], v[64:65] op_sel_hi:[0,1,1]
	v_pk_fma_f32 v[74:75], v[68:69], v[8:9], v[74:75] op_sel_hi:[0,1,1]
	v_ashrrev_i32_e32 v105, 31, v104
	v_pk_fma_f32 v[64:65], v[92:93], v[6:7], v[64:65] op_sel:[1,0,0]
	v_pk_fma_f32 v[74:75], v[92:93], v[4:5], v[74:75] op_sel:[1,0,0]
	v_lshl_add_u64 v[92:93], s[16:17], 0, v[104:105]
	v_lshlrev_b64 v[92:93], 10, v[92:93]
	v_cvt_pk_bf16_f32 v74, v74, v75
	v_cvt_pk_bf16_f32 v75, v64, v65
	v_lshl_add_u64 v[64:65], s[0:1], 0, v[92:93]
	v_lshl_add_u64 v[104:105], s[50:51], 0, v[92:93]
	v_lshl_add_u64 v[64:65], v[64:65], 0, v[2:3]
	v_lshl_add_u64 v[104:105], v[104:105], 0, v[2:3]
	global_store_dwordx2 v[64:65], v[74:75], off
	v_pk_fma_f32 v[74:75], v[20:21], v[82:83], v[36:37]
	global_store_dwordx2 v[104:105], v[90:91], off
	v_and_b32_e32 v91, 0xffff0000, v62
	v_pk_fma_f32 v[74:75], v[24:25], v[70:71], v[74:75]
	v_lshlrev_b32_e32 v64, 16, v62
	v_mov_b32_e32 v65, v91
	v_pk_fma_f32 v[74:75], v[28:29], v[66:67], v[74:75]
	v_and_b32_e32 v93, 0xffff0000, v63
	v_pk_fma_f32 v[74:75], v[32:33], v[64:65], v[74:75]
	s_movk_i32 s2, 0x60
	v_mul_f32_e32 v59, 0xbfb8aa3b, v74
	v_exp_f32_e32 v59, v59
	v_and_b32_e32 v90, 16, v62
	v_and_b32_e32 v92, 16, v63
	v_pk_fma_f32 v[70:71], v[20:21], v[70:71], v[36:37]
	v_add_f32_e32 v59, 1.0, v59
	v_rcp_f32_e32 v82, v59
	v_mul_f32_e32 v59, 0xbfb8aa3b, v75
	v_exp_f32_e32 v59, v59
	v_pk_fma_f32 v[70:71], v[24:25], v[66:67], v[70:71]
	v_pk_fma_f32 v[68:69], v[22:23], v[68:69], v[38:39]
	v_pk_fma_f32 v[70:71], v[28:29], v[64:65], v[70:71]
	v_add_f32_e32 v59, 1.0, v59
	v_rcp_f32_e32 v83, v59
	s_nop 0
	v_pk_mul_f32 v[82:83], v[74:75], v[82:83]
	v_lshlrev_b32_e32 v74, 16, v63
	v_mov_b32_e32 v75, v93
	v_pk_fma_f32 v[80:81], v[34:35], v[74:75], v[80:81]
	v_cvt_pk_bf16_f32 v82, v82, v83
	v_mul_f32_e32 v59, 0xbfb8aa3b, v80
	v_exp_f32_e32 v59, v59
	v_pk_fma_f32 v[72:73], v[30:31], v[74:75], v[72:73]
	v_pk_fma_f32 v[68:69], v[26:27], v[74:75], v[68:69]
	v_add_f32_e32 v59, 1.0, v59
	v_rcp_f32_e32 v104, v59
	v_mul_f32_e32 v59, 0xbfb8aa3b, v81
	v_exp_f32_e32 v59, v59
	s_nop 0
	v_add_f32_e32 v59, 1.0, v59
	v_rcp_f32_e32 v105, v59
	s_nop 0
	v_pk_mul_f32 v[80:81], v[80:81], v[104:105]
	v_or_b32_e32 v104, 6, v40
	v_cvt_pk_bf16_f32 v83, v80, v81
	v_lshl_add_u32 v59, v104, 11, 0
	v_bitop3_b32 v80, v58, s2, v94 bitop3:0x6c
	v_add3_u32 v59, v59, v80, v41
	ds_write2st64_b64 v59, v[82:83], v[62:63] offset1:2
	v_pk_mul_f32 v[62:63], v[90:91], v[18:19] op_sel:[1,0]
	v_pk_mul_f32 v[90:91], v[90:91], v[16:17] op_sel:[1,0]
	v_pk_fma_f32 v[62:63], v[64:65], v[14:15], v[62:63] op_sel_hi:[0,1,1]
	v_pk_fma_f32 v[90:91], v[64:65], v[12:13], v[90:91] op_sel_hi:[0,1,1]
	v_pk_fma_f32 v[62:63], v[74:75], v[10:11], v[62:63] op_sel_hi:[0,1,1]
	v_pk_fma_f32 v[90:91], v[74:75], v[8:9], v[90:91] op_sel_hi:[0,1,1]
	v_ashrrev_i32_e32 v105, 31, v104
	v_pk_fma_f32 v[62:63], v[92:93], v[6:7], v[62:63] op_sel:[1,0,0]
	v_pk_fma_f32 v[90:91], v[92:93], v[4:5], v[90:91] op_sel:[1,0,0]
	v_lshl_add_u64 v[92:93], s[16:17], 0, v[104:105]
	v_lshlrev_b64 v[92:93], 10, v[92:93]
	v_lshl_add_u64 v[104:105], s[50:51], 0, v[92:93]
	v_lshl_add_u64 v[104:105], v[104:105], 0, v[2:3]
	global_store_dwordx2 v[104:105], v[82:83], off
	v_cvt_pk_bf16_f32 v83, v62, v63
	v_lshl_add_u64 v[62:63], s[0:1], 0, v[92:93]
	v_cvt_pk_bf16_f32 v82, v90, v91
	v_lshl_add_u64 v[62:63], v[62:63], 0, v[2:3]
	global_store_dwordx2 v[62:63], v[82:83], off
	v_and_b32_e32 v83, 0xffff0000, v60
	v_lshlrev_b32_e32 v62, 16, v60
	v_mov_b32_e32 v63, v83
	v_pk_fma_f32 v[70:71], v[32:33], v[62:63], v[70:71]
	v_and_b32_e32 v93, 0xffff0000, v61
	v_mul_f32_e32 v59, 0xbfb8aa3b, v70
	v_exp_f32_e32 v59, v59
	s_movk_i32 s2, 0x70
	v_and_b32_e32 v82, 16, v60
	v_and_b32_e32 v92, 16, v61
	v_add_f32_e32 v59, 1.0, v59
	v_rcp_f32_e32 v90, v59
	v_mul_f32_e32 v59, 0xbfb8aa3b, v71
	v_exp_f32_e32 v59, v59
	v_pk_fma_f32 v[74:75], v[22:23], v[74:75], v[38:39]
	v_add_f32_e32 v59, 1.0, v59
	v_rcp_f32_e32 v91, v59
	s_nop 0
	v_pk_mul_f32 v[90:91], v[70:71], v[90:91]
	v_lshlrev_b32_e32 v70, 16, v61
	v_mov_b32_e32 v71, v93
	v_pk_fma_f32 v[72:73], v[34:35], v[70:71], v[72:73]
	v_cvt_pk_bf16_f32 v90, v90, v91
	v_mul_f32_e32 v59, 0xbfb8aa3b, v72
	v_exp_f32_e32 v59, v59
	v_pk_fma_f32 v[68:69], v[30:31], v[70:71], v[68:69]
	v_pk_fma_f32 v[74:75], v[26:27], v[70:71], v[74:75]
	v_add_f32_e32 v59, 1.0, v59
	v_rcp_f32_e32 v104, v59
	v_mul_f32_e32 v59, 0xbfb8aa3b, v73
	v_exp_f32_e32 v59, v59
	s_nop 0
	v_add_f32_e32 v59, 1.0, v59
	v_rcp_f32_e32 v105, v59
	s_nop 0
	v_pk_mul_f32 v[72:73], v[72:73], v[104:105]
	v_or_b32_e32 v104, 7, v40
	v_cvt_pk_bf16_f32 v91, v72, v73
	v_lshl_add_u32 v59, v104, 11, 0
	v_bitop3_b32 v72, v58, s2, v94 bitop3:0x6c
	v_add3_u32 v58, v59, v72, v41
	ds_write2st64_b64 v58, v[90:91], v[60:61] offset1:2
	v_pk_mul_f32 v[58:59], v[82:83], v[18:19] op_sel:[1,0]
	v_pk_mul_f32 v[60:61], v[82:83], v[16:17] op_sel:[1,0]
	v_pk_fma_f32 v[58:59], v[62:63], v[14:15], v[58:59] op_sel_hi:[0,1,1]
	v_pk_fma_f32 v[60:61], v[62:63], v[12:13], v[60:61] op_sel_hi:[0,1,1]
	v_ashrrev_i32_e32 v105, 31, v104
	v_pk_fma_f32 v[58:59], v[70:71], v[10:11], v[58:59] op_sel_hi:[0,1,1]
	v_pk_fma_f32 v[60:61], v[70:71], v[8:9], v[60:61] op_sel_hi:[0,1,1]
	v_lshl_add_u64 v[82:83], s[16:17], 0, v[104:105]
	v_pk_fma_f32 v[58:59], v[92:93], v[6:7], v[58:59] op_sel:[1,0,0]
	v_pk_fma_f32 v[60:61], v[92:93], v[4:5], v[60:61] op_sel:[1,0,0]
	v_lshlrev_b64 v[82:83], 10, v[82:83]
	v_cvt_pk_bf16_f32 v60, v60, v61
	v_cvt_pk_bf16_f32 v61, v58, v59
	v_lshl_add_u64 v[58:59], s[0:1], 0, v[82:83]
	v_lshl_add_u64 v[58:59], v[58:59], 0, v[2:3]
; #define GAS __attribute__((address_space(1)))
; #define LAS __attribute__((address_space(3)))
; __device__ __forceinline__ float fsigmoid(float x) { return __builtin_amdgcn_rcpf(1.f + __builtin_amdgcn_exp2f(-LOG2E * x)); }
; __device__ __forceinline__ f32x4 bf4_to_f32(u32x2 w) { return (f32x4){bflo(w.x), bfhi(w.x), bflo(w.y), bfhi(w.y)}; }
; __device__ __forceinline__ u32x2 f32_to_bf4(f32x4 v) { u32x2 w; w.x = cvtpk(v[0], v[1]); w.y = cvtpk(v[2], v[3]); return w; }
; __device__ __forceinline__ void prep_unit(LAS unsigned char* lds, const MixBufs& B, int b, int ch, int tid) {
;     ...
;         for (int s = 0; s < 16; ++s) { const int row = 16 * strip + s;
;             const f32x4 x0 = bf4_to_f32(xr[s + 3]);
;             f32x4 cv = cb + cw[0] * x3 + cw[1] * x2 + cw[2] * x1 + cw[3] * x0, xc;
; #pragma unroll
;             for (int e = 0; e < 4; ++e) xc[e] = cv[e] * fsigmoid(cv[e]);
;             const int sw = row & 7, within = (gch & 1) * 8;
;             *(LAS u32x2*)(XA + row * 2048 + ((((gch >> 1)) ^ sw) << 4) + within) = f32_to_bf4(xc);
;             *(LAS u32x2*)(XA + row * 2048 + (((64 + (gch >> 1)) ^ sw) << 4) + within) = xr[s + 3];
;             const f32x4 v = wv[0] * x0[0] + wv[1] * x0[1] + wv[2] * x0[2] + wv[3] * x0[3];
;             *(GAS u32x2*)(B.xcm + (t0 + row) * 512 + 4 * gch) = f32_to_bf4(xc); *(GAS u32x2*)(B.vm + (t0 + row) * 512 + 4 * gch) = f32_to_bf4(v);
;             x3 = x2; x2 = x1; x1 = x0; }
	global_store_dwordx2 v[58:59], v[60:61], off
	v_pk_fma_f32 v[60:61], v[20:21], v[66:67], v[36:37]
	v_lshl_add_u64 v[92:93], s[50:51], 0, v[82:83]
	v_and_b32_e32 v83, 0xffff0000, v56
	v_pk_fma_f32 v[60:61], v[24:25], v[64:65], v[60:61]
	v_lshlrev_b32_e32 v58, 16, v56
	v_mov_b32_e32 v59, v83
	v_pk_fma_f32 v[60:61], v[28:29], v[62:63], v[60:61]
	v_lshl_add_u64 v[92:93], v[92:93], 0, v[2:3]
	v_pk_fma_f32 v[60:61], v[32:33], v[58:59], v[60:61]
	global_store_dwordx2 v[92:93], v[90:91], off
	v_mul_f32_e32 v66, 0xbfb8aa3b, v60
	v_mul_f32_e32 v67, 0xbfb8aa3b, v61
	v_exp_f32_e32 v66, v66
	v_exp_f32_e32 v67, v67
	v_and_b32_e32 v91, 0xffff0000, v57
	v_and_b32_e32 v82, 16, v56
	v_add_f32_e32 v66, 1.0, v66
	v_add_f32_e32 v67, 1.0, v67
	v_rcp_f32_e32 v66, v66
	v_rcp_f32_e32 v67, v67
	v_and_b32_e32 v90, 16, v57
	v_pk_fma_f32 v[64:65], v[20:21], v[64:65], v[36:37]
	v_pk_fma_f32 v[70:71], v[22:23], v[70:71], v[38:39]
	v_pk_mul_f32 v[66:67], v[60:61], v[66:67]
	v_lshlrev_b32_e32 v60, 16, v57
	v_mov_b32_e32 v61, v91
	v_pk_fma_f32 v[68:69], v[34:35], v[60:61], v[68:69]
	v_cvt_pk_bf16_f32 v66, v66, v67
	v_mul_f32_e32 v73, 0xbfb8aa3b, v68
	v_exp_f32_e32 v73, v73
	v_pk_fma_f32 v[64:65], v[24:25], v[62:63], v[64:65]
	v_pk_fma_f32 v[74:75], v[30:31], v[60:61], v[74:75]
	v_pk_fma_f32 v[64:65], v[28:29], v[58:59], v[64:65]
	v_add_f32_e32 v73, 1.0, v73
	v_rcp_f32_e32 v92, v73
	v_mul_f32_e32 v73, 0xbfb8aa3b, v69
	v_exp_f32_e32 v73, v73
	v_pk_fma_f32 v[62:63], v[20:21], v[62:63], v[36:37]
	v_pk_fma_f32 v[70:71], v[26:27], v[60:61], v[70:71]
	v_pk_fma_f32 v[62:63], v[24:25], v[58:59], v[62:63]
	v_add_f32_e32 v73, 1.0, v73
	v_rcp_f32_e32 v93, v73
	s_lshl_b32 s2, s18, 2
	v_pk_mul_f32 v[68:69], v[68:69], v[92:93]
	v_or_b32_e32 v92, 8, v40
	v_cvt_pk_bf16_f32 v67, v68, v69
	v_lshl_add_u32 v68, v92, 11, 0
	v_add3_u32 v68, v68, v101, v41
	ds_write2st64_b64 v68, v[66:67], v[56:57] offset1:2
	v_pk_mul_f32 v[56:57], v[82:83], v[18:19] op_sel:[1,0]
	v_pk_mul_f32 v[68:69], v[82:83], v[16:17] op_sel:[1,0]
	v_ashrrev_i32_e32 v93, 31, v92
	v_pk_fma_f32 v[56:57], v[58:59], v[14:15], v[56:57] op_sel_hi:[0,1,1]
	v_pk_fma_f32 v[68:69], v[58:59], v[12:13], v[68:69] op_sel_hi:[0,1,1]
	v_lshl_add_u64 v[82:83], s[16:17], 0, v[92:93]
	v_pk_fma_f32 v[56:57], v[60:61], v[10:11], v[56:57] op_sel_hi:[0,1,1]
	v_pk_fma_f32 v[68:69], v[60:61], v[8:9], v[68:69] op_sel_hi:[0,1,1]
	v_lshlrev_b64 v[82:83], 10, v[82:83]
	v_pk_fma_f32 v[56:57], v[90:91], v[6:7], v[56:57] op_sel:[1,0,0]
	v_pk_fma_f32 v[68:69], v[90:91], v[4:5], v[68:69] op_sel:[1,0,0]
	v_lshl_add_u64 v[90:91], s[50:51], 0, v[82:83]
	v_lshl_add_u64 v[90:91], v[90:91], 0, v[2:3]
	global_store_dwordx2 v[90:91], v[66:67], off
	v_cvt_pk_bf16_f32 v67, v56, v57
	v_lshl_add_u64 v[56:57], s[0:1], 0, v[82:83]
	v_cvt_pk_bf16_f32 v66, v68, v69
	v_lshl_add_u64 v[56:57], v[56:57], 0, v[2:3]
	global_store_dwordx2 v[56:57], v[66:67], off
	v_and_b32_e32 v67, 0xffff0000, v54
	v_lshlrev_b32_e32 v56, 16, v54
	v_mov_b32_e32 v57, v67
	v_pk_fma_f32 v[64:65], v[32:33], v[56:57], v[64:65]
	v_and_b32_e32 v83, 0xffff0000, v55
	v_mul_f32_e32 v68, 0xbfb8aa3b, v64
	v_mul_f32_e32 v69, 0xbfb8aa3b, v65
	v_exp_f32_e32 v68, v68
	v_exp_f32_e32 v69, v69
	v_and_b32_e32 v66, 16, v54
	v_and_b32_e32 v82, 16, v55
	v_add_f32_e32 v68, 1.0, v68
	v_add_f32_e32 v69, 1.0, v69
	v_rcp_f32_e32 v68, v68
	v_rcp_f32_e32 v69, v69
	v_pk_fma_f32 v[62:63], v[28:29], v[56:57], v[62:63]
	v_pk_fma_f32 v[58:59], v[20:21], v[58:59], v[36:37]
	v_pk_fma_f32 v[60:61], v[22:23], v[60:61], v[38:39]
	v_pk_mul_f32 v[68:69], v[64:65], v[68:69]
	v_lshlrev_b32_e32 v64, 16, v55
	v_mov_b32_e32 v65, v83
	v_pk_fma_f32 v[74:75], v[34:35], v[64:65], v[74:75]
	v_cvt_pk_bf16_f32 v68, v68, v69
	v_mul_f32_e32 v73, 0xbfb8aa3b, v74
	v_exp_f32_e32 v73, v73
	v_pk_fma_f32 v[70:71], v[30:31], v[64:65], v[70:71]
	v_pk_fma_f32 v[58:59], v[24:25], v[56:57], v[58:59]
	v_pk_fma_f32 v[60:61], v[26:27], v[64:65], v[60:61]
	v_add_f32_e32 v73, 1.0, v73
	v_rcp_f32_e32 v90, v73
	v_mul_f32_e32 v73, 0xbfb8aa3b, v75
	v_exp_f32_e32 v73, v73
	s_nop 0
	v_add_f32_e32 v73, 1.0, v73
	v_rcp_f32_e32 v91, v73
	s_nop 0
	v_pk_mul_f32 v[74:75], v[74:75], v[90:91]
	v_or_b32_e32 v90, 9, v40
	v_lshl_add_u32 v73, v90, 11, 0
	v_cvt_pk_bf16_f32 v69, v74, v75
	v_add3_u32 v73, v73, v102, v41
	ds_write2st64_b64 v73, v[68:69], v[54:55] offset1:2
	v_pk_mul_f32 v[54:55], v[66:67], v[18:19] op_sel:[1,0]
	v_pk_mul_f32 v[66:67], v[66:67], v[16:17] op_sel:[1,0]
	v_pk_fma_f32 v[54:55], v[56:57], v[14:15], v[54:55] op_sel_hi:[0,1,1]
	v_pk_fma_f32 v[66:67], v[56:57], v[12:13], v[66:67] op_sel_hi:[0,1,1]
	v_ashrrev_i32_e32 v91, 31, v90
	v_pk_fma_f32 v[54:55], v[64:65], v[10:11], v[54:55] op_sel_hi:[0,1,1]
	v_pk_fma_f32 v[66:67], v[64:65], v[8:9], v[66:67] op_sel_hi:[0,1,1]
	v_lshl_add_u64 v[74:75], s[16:17], 0, v[90:91]
	v_pk_fma_f32 v[54:55], v[82:83], v[6:7], v[54:55] op_sel:[1,0,0]
	v_pk_fma_f32 v[66:67], v[82:83], v[4:5], v[66:67] op_sel:[1,0,0]
	v_lshlrev_b64 v[74:75], 10, v[74:75]
	v_cvt_pk_bf16_f32 v66, v66, v67
	v_cvt_pk_bf16_f32 v67, v54, v55
	v_lshl_add_u64 v[54:55], s[0:1], 0, v[74:75]
	v_lshl_add_u64 v[54:55], v[54:55], 0, v[2:3]
	global_store_dwordx2 v[54:55], v[66:67], off
	v_and_b32_e32 v67, 0xffff0000, v52
	v_lshl_add_u64 v[82:83], s[50:51], 0, v[74:75]
	v_lshlrev_b32_e32 v54, 16, v52
	v_mov_b32_e32 v55, v67
	v_lshl_add_u64 v[82:83], v[82:83], 0, v[2:3]
	v_pk_fma_f32 v[62:63], v[32:33], v[54:55], v[62:63]
	global_store_dwordx2 v[82:83], v[68:69], off
	v_mul_f32_e32 v68, 0xbfb8aa3b, v62
	v_mul_f32_e32 v69, 0xbfb8aa3b, v63
	v_exp_f32_e32 v68, v68
	v_exp_f32_e32 v69, v69
	v_and_b32_e32 v75, 0xffff0000, v53
	v_and_b32_e32 v66, 16, v52
	v_add_f32_e32 v68, 1.0, v68
; #define GAS __attribute__((address_space(1)))
; #define LAS __attribute__((address_space(3)))
; __device__ __forceinline__ float fsigmoid(float x) { return __builtin_amdgcn_rcpf(1.f + __builtin_amdgcn_exp2f(-LOG2E * x)); }
; __device__ __forceinline__ f32x4 bf4_to_f32(u32x2 w) { return (f32x4){bflo(w.x), bfhi(w.x), bflo(w.y), bfhi(w.y)}; }
; __device__ __forceinline__ u32x2 f32_to_bf4(f32x4 v) { u32x2 w; w.x = cvtpk(v[0], v[1]); w.y = cvtpk(v[2], v[3]); return w; }
; __device__ __forceinline__ void prep_unit(LAS unsigned char* lds, const MixBufs& B, int b, int ch, int tid) {
;     ...
;         for (int s = 0; s < 16; ++s) { const int row = 16 * strip + s;
;             const f32x4 x0 = bf4_to_f32(xr[s + 3]);
;             f32x4 cv = cb + cw[0] * x3 + cw[1] * x2 + cw[2] * x1 + cw[3] * x0, xc;
; #pragma unroll
;             for (int e = 0; e < 4; ++e) xc[e] = cv[e] * fsigmoid(cv[e]);
;             const int sw = row & 7, within = (gch & 1) * 8;
;             *(LAS u32x2*)(XA + row * 2048 + ((((gch >> 1)) ^ sw) << 4) + within) = f32_to_bf4(xc);
;             *(LAS u32x2*)(XA + row * 2048 + (((64 + (gch >> 1)) ^ sw) << 4) + within) = xr[s + 3];
;             const f32x4 v = wv[0] * x0[0] + wv[1] * x0[1] + wv[2] * x0[2] + wv[3] * x0[3];
;             *(GAS u32x2*)(B.xcm + (t0 + row) * 512 + 4 * gch) = f32_to_bf4(xc); *(GAS u32x2*)(B.vm + (t0 + row) * 512 + 4 * gch) = f32_to_bf4(v);
;             x3 = x2; x2 = x1; x1 = x0; }
	v_add_f32_e32 v69, 1.0, v69
	v_rcp_f32_e32 v68, v68
	v_rcp_f32_e32 v69, v69
	v_and_b32_e32 v74, 16, v53
	v_pk_fma_f32 v[58:59], v[28:29], v[54:55], v[58:59]
	v_pk_fma_f32 v[56:57], v[20:21], v[56:57], v[36:37]
	v_pk_mul_f32 v[68:69], v[62:63], v[68:69]
	v_lshlrev_b32_e32 v62, 16, v53
	v_mov_b32_e32 v63, v75
	v_pk_fma_f32 v[70:71], v[34:35], v[62:63], v[70:71]
	v_cvt_pk_bf16_f32 v68, v68, v69
	v_mul_f32_e32 v73, 0xbfb8aa3b, v70
	v_exp_f32_e32 v73, v73
	v_pk_fma_f32 v[60:61], v[30:31], v[62:63], v[60:61]
	v_pk_fma_f32 v[56:57], v[24:25], v[54:55], v[56:57]
	v_pk_fma_f32 v[64:65], v[22:23], v[64:65], v[38:39]
	v_add_f32_e32 v73, 1.0, v73
	v_rcp_f32_e32 v82, v73
	v_mul_f32_e32 v73, 0xbfb8aa3b, v71
	v_exp_f32_e32 v73, v73
	v_pk_fma_f32 v[64:65], v[26:27], v[62:63], v[64:65]
	v_add_f32_e32 v73, 1.0, v73
	v_rcp_f32_e32 v83, v73
	s_nop 0
	v_pk_mul_f32 v[70:71], v[70:71], v[82:83]
	v_or_b32_e32 v82, 10, v40
	v_cvt_pk_bf16_f32 v69, v70, v71
	v_lshl_add_u32 v70, v82, 11, 0
	v_add3_u32 v70, v70, v88, v41
	ds_write2st64_b64 v70, v[68:69], v[52:53] offset1:2
	v_pk_mul_f32 v[52:53], v[66:67], v[18:19] op_sel:[1,0]
	v_pk_mul_f32 v[66:67], v[66:67], v[16:17] op_sel:[1,0]
	v_pk_fma_f32 v[52:53], v[54:55], v[14:15], v[52:53] op_sel_hi:[0,1,1]
	v_pk_fma_f32 v[66:67], v[54:55], v[12:13], v[66:67] op_sel_hi:[0,1,1]
	v_ashrrev_i32_e32 v83, 31, v82
	v_pk_fma_f32 v[52:53], v[62:63], v[10:11], v[52:53] op_sel_hi:[0,1,1]
	v_pk_fma_f32 v[66:67], v[62:63], v[8:9], v[66:67] op_sel_hi:[0,1,1]
	v_lshl_add_u64 v[70:71], s[16:17], 0, v[82:83]
	v_pk_fma_f32 v[52:53], v[74:75], v[6:7], v[52:53] op_sel:[1,0,0]
	v_pk_fma_f32 v[66:67], v[74:75], v[4:5], v[66:67] op_sel:[1,0,0]
	v_lshlrev_b64 v[70:71], 10, v[70:71]
	v_cvt_pk_bf16_f32 v66, v66, v67
	v_cvt_pk_bf16_f32 v67, v52, v53
	v_lshl_add_u64 v[52:53], s[0:1], 0, v[70:71]
	v_lshl_add_u64 v[52:53], v[52:53], 0, v[2:3]
	global_store_dwordx2 v[52:53], v[66:67], off
	v_and_b32_e32 v67, 0xffff0000, v50
	v_lshl_add_u64 v[74:75], s[50:51], 0, v[70:71]
	v_lshlrev_b32_e32 v52, 16, v50
	v_mov_b32_e32 v53, v67
	v_lshl_add_u64 v[74:75], v[74:75], 0, v[2:3]
	v_pk_fma_f32 v[58:59], v[32:33], v[52:53], v[58:59]
	global_store_dwordx2 v[74:75], v[68:69], off
	v_mul_f32_e32 v68, 0xbfb8aa3b, v58
	v_mul_f32_e32 v69, 0xbfb8aa3b, v59
	v_exp_f32_e32 v68, v68
	v_exp_f32_e32 v69, v69
	v_and_b32_e32 v71, 0xffff0000, v51
	v_and_b32_e32 v66, 16, v50
	v_add_f32_e32 v68, 1.0, v68
	v_add_f32_e32 v69, 1.0, v69
	v_rcp_f32_e32 v68, v68
	v_rcp_f32_e32 v69, v69
	v_and_b32_e32 v70, 16, v51
	v_pk_fma_f32 v[56:57], v[28:29], v[52:53], v[56:57]
	v_pk_fma_f32 v[54:55], v[20:21], v[54:55], v[36:37]
	v_pk_mul_f32 v[68:69], v[58:59], v[68:69]
	v_lshlrev_b32_e32 v58, 16, v51
	v_mov_b32_e32 v59, v71
	v_pk_fma_f32 v[60:61], v[34:35], v[58:59], v[60:61]
	v_cvt_pk_bf16_f32 v68, v68, v69
	v_mul_f32_e32 v73, 0xbfb8aa3b, v60
	v_exp_f32_e32 v73, v73
	v_pk_fma_f32 v[64:65], v[30:31], v[58:59], v[64:65]
	v_pk_fma_f32 v[54:55], v[24:25], v[52:53], v[54:55]
	v_pk_fma_f32 v[62:63], v[22:23], v[62:63], v[38:39]
	v_add_f32_e32 v73, 1.0, v73
	v_rcp_f32_e32 v74, v73
	v_mul_f32_e32 v73, 0xbfb8aa3b, v61
	v_exp_f32_e32 v73, v73
	v_pk_fma_f32 v[62:63], v[26:27], v[58:59], v[62:63]
	v_add_f32_e32 v73, 1.0, v73
	v_rcp_f32_e32 v75, v73
	s_nop 0
	v_pk_mul_f32 v[60:61], v[60:61], v[74:75]
	v_or_b32_e32 v74, 11, v40
	v_cvt_pk_bf16_f32 v69, v60, v61
	v_lshl_add_u32 v60, v74, 11, 0
	v_add3_u32 v60, v60, v84, v41
	ds_write2st64_b64 v60, v[68:69], v[50:51] offset1:2
	v_pk_mul_f32 v[50:51], v[66:67], v[18:19] op_sel:[1,0]
	v_pk_mul_f32 v[60:61], v[66:67], v[16:17] op_sel:[1,0]
	v_pk_fma_f32 v[50:51], v[52:53], v[14:15], v[50:51] op_sel_hi:[0,1,1]
	v_pk_fma_f32 v[60:61], v[52:53], v[12:13], v[60:61] op_sel_hi:[0,1,1]
	v_ashrrev_i32_e32 v75, 31, v74
	v_pk_fma_f32 v[50:51], v[58:59], v[10:11], v[50:51] op_sel_hi:[0,1,1]
	v_pk_fma_f32 v[60:61], v[58:59], v[8:9], v[60:61] op_sel_hi:[0,1,1]
	v_lshl_add_u64 v[66:67], s[16:17], 0, v[74:75]
	v_pk_fma_f32 v[50:51], v[70:71], v[6:7], v[50:51] op_sel:[1,0,0]
	v_pk_fma_f32 v[60:61], v[70:71], v[4:5], v[60:61] op_sel:[1,0,0]
	v_lshlrev_b64 v[66:67], 10, v[66:67]
	v_cvt_pk_bf16_f32 v60, v60, v61
	v_cvt_pk_bf16_f32 v61, v50, v51
	v_lshl_add_u64 v[50:51], s[0:1], 0, v[66:67]
	v_lshl_add_u64 v[50:51], v[50:51], 0, v[2:3]
	global_store_dwordx2 v[50:51], v[60:61], off
	v_and_b32_e32 v61, 0xffff0000, v48
	v_lshlrev_b32_e32 v50, 16, v48
	v_mov_b32_e32 v51, v61
	v_pk_fma_f32 v[56:57], v[32:33], v[50:51], v[56:57]
	v_lshl_add_u64 v[70:71], s[50:51], 0, v[66:67]
	v_mul_f32_e32 v66, 0xbfb8aa3b, v56
	v_mul_f32_e32 v67, 0xbfb8aa3b, v57
	v_exp_f32_e32 v66, v66
	v_exp_f32_e32 v67, v67
	v_lshl_add_u64 v[70:71], v[70:71], 0, v[2:3]
	global_store_dwordx2 v[70:71], v[68:69], off
	v_add_f32_e32 v66, 1.0, v66
	v_add_f32_e32 v67, 1.0, v67
	v_rcp_f32_e32 v66, v66
	v_rcp_f32_e32 v67, v67
	v_and_b32_e32 v69, 0xffff0000, v49
	v_and_b32_e32 v60, 16, v48
	v_and_b32_e32 v68, 16, v49
	v_pk_mul_f32 v[66:67], v[56:57], v[66:67]
	v_lshlrev_b32_e32 v56, 16, v49
	v_mov_b32_e32 v57, v69
	v_pk_fma_f32 v[64:65], v[34:35], v[56:57], v[64:65]
	v_cvt_pk_bf16_f32 v66, v66, v67
	v_mul_f32_e32 v70, 0xbfb8aa3b, v64
	v_mul_f32_e32 v71, 0xbfb8aa3b, v65
	v_exp_f32_e32 v70, v70
	v_exp_f32_e32 v71, v71
	v_pk_fma_f32 v[54:55], v[28:29], v[50:51], v[54:55]
	v_pk_fma_f32 v[62:63], v[30:31], v[56:57], v[62:63]
	v_add_f32_e32 v70, 1.0, v70
	v_add_f32_e32 v71, 1.0, v71
	v_rcp_f32_e32 v70, v70
	v_rcp_f32_e32 v71, v71
	v_pk_fma_f32 v[52:53], v[20:21], v[52:53], v[36:37]
	v_pk_fma_f32 v[58:59], v[22:23], v[58:59], v[38:39]
	v_pk_fma_f32 v[52:53], v[24:25], v[50:51], v[52:53]
	v_pk_mul_f32 v[64:65], v[64:65], v[70:71]
; #define GAS __attribute__((address_space(1)))
; #define LAS __attribute__((address_space(3)))
; __device__ __forceinline__ float fsigmoid(float x) { return __builtin_amdgcn_rcpf(1.f + __builtin_amdgcn_exp2f(-LOG2E * x)); }
; __device__ __forceinline__ f32x4 bf4_to_f32(u32x2 w) { return (f32x4){bflo(w.x), bfhi(w.x), bflo(w.y), bfhi(w.y)}; }
; __device__ __forceinline__ u32x2 f32_to_bf4(f32x4 v) { u32x2 w; w.x = cvtpk(v[0], v[1]); w.y = cvtpk(v[2], v[3]); return w; }
; __device__ __forceinline__ void prep_unit(LAS unsigned char* lds, const MixBufs& B, int b, int ch, int tid) {
;     ...
;         for (int s = 0; s < 16; ++s) { const int row = 16 * strip + s;
;             const f32x4 x0 = bf4_to_f32(xr[s + 3]);
;             f32x4 cv = cb + cw[0] * x3 + cw[1] * x2 + cw[2] * x1 + cw[3] * x0, xc;
; #pragma unroll
;             for (int e = 0; e < 4; ++e) xc[e] = cv[e] * fsigmoid(cv[e]);
;             const int sw = row & 7, within = (gch & 1) * 8;
;             *(LAS u32x2*)(XA + row * 2048 + ((((gch >> 1)) ^ sw) << 4) + within) = f32_to_bf4(xc);
;             *(LAS u32x2*)(XA + row * 2048 + (((64 + (gch >> 1)) ^ sw) << 4) + within) = xr[s + 3];
;             const f32x4 v = wv[0] * x0[0] + wv[1] * x0[1] + wv[2] * x0[2] + wv[3] * x0[3];
;             *(GAS u32x2*)(B.xcm + (t0 + row) * 512 + 4 * gch) = f32_to_bf4(xc); *(GAS u32x2*)(B.vm + (t0 + row) * 512 + 4 * gch) = f32_to_bf4(v);
;             x3 = x2; x2 = x1; x1 = x0; }
	v_or_b32_e32 v70, 12, v40
	v_cvt_pk_bf16_f32 v67, v64, v65
	v_lshl_add_u32 v64, v70, 11, 0
	v_add3_u32 v64, v64, v85, v41
	ds_write2st64_b64 v64, v[66:67], v[48:49] offset1:2
	v_pk_mul_f32 v[48:49], v[60:61], v[18:19] op_sel:[1,0]
	v_pk_mul_f32 v[60:61], v[60:61], v[16:17] op_sel:[1,0]
	v_pk_fma_f32 v[48:49], v[50:51], v[14:15], v[48:49] op_sel_hi:[0,1,1]
	v_pk_fma_f32 v[60:61], v[50:51], v[12:13], v[60:61] op_sel_hi:[0,1,1]
	v_ashrrev_i32_e32 v71, 31, v70
	v_pk_fma_f32 v[48:49], v[56:57], v[10:11], v[48:49] op_sel_hi:[0,1,1]
	v_pk_fma_f32 v[60:61], v[56:57], v[8:9], v[60:61] op_sel_hi:[0,1,1]
	v_lshl_add_u64 v[64:65], s[16:17], 0, v[70:71]
	v_pk_fma_f32 v[48:49], v[68:69], v[6:7], v[48:49] op_sel:[1,0,0]
	v_pk_fma_f32 v[60:61], v[68:69], v[4:5], v[60:61] op_sel:[1,0,0]
	v_lshlrev_b64 v[64:65], 10, v[64:65]
	v_cvt_pk_bf16_f32 v60, v60, v61
	v_cvt_pk_bf16_f32 v61, v48, v49
	v_lshl_add_u64 v[48:49], s[0:1], 0, v[64:65]
	v_lshl_add_u64 v[48:49], v[48:49], 0, v[2:3]
	global_store_dwordx2 v[48:49], v[60:61], off
	v_and_b32_e32 v61, 0xffff0000, v46
	v_lshlrev_b32_e32 v48, 16, v46
	v_mov_b32_e32 v49, v61
	v_pk_fma_f32 v[54:55], v[32:33], v[48:49], v[54:55]
	v_lshl_add_u64 v[68:69], s[50:51], 0, v[64:65]
	v_mul_f32_e32 v64, 0xbfb8aa3b, v54
	v_mul_f32_e32 v65, 0xbfb8aa3b, v55
	v_exp_f32_e32 v64, v64
	v_exp_f32_e32 v65, v65
	v_lshl_add_u64 v[68:69], v[68:69], 0, v[2:3]
	global_store_dwordx2 v[68:69], v[66:67], off
	v_add_f32_e32 v64, 1.0, v64
	v_add_f32_e32 v65, 1.0, v65
	v_rcp_f32_e32 v64, v64
	v_rcp_f32_e32 v65, v65
	v_and_b32_e32 v67, 0xffff0000, v47
	v_and_b32_e32 v60, 16, v46
	v_and_b32_e32 v66, 16, v47
	v_pk_mul_f32 v[64:65], v[54:55], v[64:65]
	v_lshlrev_b32_e32 v54, 16, v47
	v_mov_b32_e32 v55, v67
	v_pk_fma_f32 v[62:63], v[34:35], v[54:55], v[62:63]
	v_cvt_pk_bf16_f32 v64, v64, v65
	v_mul_f32_e32 v68, 0xbfb8aa3b, v62
	v_mul_f32_e32 v69, 0xbfb8aa3b, v63
	v_exp_f32_e32 v68, v68
	v_exp_f32_e32 v69, v69
	v_pk_fma_f32 v[52:53], v[28:29], v[48:49], v[52:53]
	v_pk_fma_f32 v[58:59], v[26:27], v[56:57], v[58:59]
	v_add_f32_e32 v68, 1.0, v68
	v_add_f32_e32 v69, 1.0, v69
	v_rcp_f32_e32 v68, v68
	v_rcp_f32_e32 v69, v69
	v_pk_fma_f32 v[58:59], v[30:31], v[54:55], v[58:59]
	v_pk_fma_f32 v[20:21], v[20:21], v[50:51], v[36:37]
	v_pk_fma_f32 v[22:23], v[22:23], v[56:57], v[38:39]
	v_pk_mul_f32 v[62:63], v[62:63], v[68:69]
	v_or_b32_e32 v68, 13, v40
	v_cvt_pk_bf16_f32 v65, v62, v63
	v_lshl_add_u32 v62, v68, 11, 0
	v_add3_u32 v62, v62, v86, v41
	ds_write2st64_b64 v62, v[64:65], v[46:47] offset1:2
	v_pk_mul_f32 v[46:47], v[60:61], v[18:19] op_sel:[1,0]
	v_pk_mul_f32 v[60:61], v[60:61], v[16:17] op_sel:[1,0]
	v_pk_fma_f32 v[46:47], v[48:49], v[14:15], v[46:47] op_sel_hi:[0,1,1]
	v_pk_fma_f32 v[60:61], v[48:49], v[12:13], v[60:61] op_sel_hi:[0,1,1]
	v_ashrrev_i32_e32 v69, 31, v68
	v_pk_fma_f32 v[46:47], v[54:55], v[10:11], v[46:47] op_sel_hi:[0,1,1]
	v_pk_fma_f32 v[60:61], v[54:55], v[8:9], v[60:61] op_sel_hi:[0,1,1]
	v_lshl_add_u64 v[62:63], s[16:17], 0, v[68:69]
	v_pk_fma_f32 v[46:47], v[66:67], v[6:7], v[46:47] op_sel:[1,0,0]
	v_pk_fma_f32 v[60:61], v[66:67], v[4:5], v[60:61] op_sel:[1,0,0]
	v_lshlrev_b64 v[62:63], 10, v[62:63]
	v_cvt_pk_bf16_f32 v60, v60, v61
	v_cvt_pk_bf16_f32 v61, v46, v47
	v_lshl_add_u64 v[46:47], s[0:1], 0, v[62:63]
	v_lshl_add_u64 v[46:47], v[46:47], 0, v[2:3]
	global_store_dwordx2 v[46:47], v[60:61], off
	v_and_b32_e32 v61, 0xffff0000, v44
	v_lshlrev_b32_e32 v46, 16, v44
	v_mov_b32_e32 v47, v61
	v_pk_fma_f32 v[52:53], v[32:33], v[46:47], v[52:53]
	v_lshl_add_u64 v[66:67], s[50:51], 0, v[62:63]
	v_mul_f32_e32 v62, 0xbfb8aa3b, v52
	v_mul_f32_e32 v63, 0xbfb8aa3b, v53
	v_exp_f32_e32 v62, v62
	v_exp_f32_e32 v63, v63
	v_lshl_add_u64 v[66:67], v[66:67], 0, v[2:3]
	global_store_dwordx2 v[66:67], v[64:65], off
	v_add_f32_e32 v62, 1.0, v62
	v_add_f32_e32 v63, 1.0, v63
	v_rcp_f32_e32 v62, v62
	v_rcp_f32_e32 v63, v63
	v_and_b32_e32 v65, 0xffff0000, v45
	v_and_b32_e32 v60, 16, v44
	v_and_b32_e32 v64, 16, v45
	v_pk_mul_f32 v[52:53], v[52:53], v[62:63]
	v_lshlrev_b32_e32 v62, 16, v45
	v_mov_b32_e32 v63, v65
	v_pk_fma_f32 v[58:59], v[34:35], v[62:63], v[58:59]
	v_cvt_pk_bf16_f32 v52, v52, v53
	v_mul_f32_e32 v66, 0xbfb8aa3b, v58
	v_mul_f32_e32 v67, 0xbfb8aa3b, v59
	v_exp_f32_e32 v66, v66
	v_exp_f32_e32 v67, v67
	v_pk_fma_f32 v[20:21], v[24:25], v[48:49], v[20:21]
	v_pk_fma_f32 v[22:23], v[26:27], v[54:55], v[22:23]
	v_add_f32_e32 v66, 1.0, v66
	v_add_f32_e32 v67, 1.0, v67
	v_rcp_f32_e32 v66, v66
	v_rcp_f32_e32 v67, v67
	v_pk_fma_f32 v[20:21], v[28:29], v[46:47], v[20:21]
	v_and_b32_e32 v29, 0xffff0000, v43
	v_pk_fma_f32 v[22:23], v[30:31], v[62:63], v[22:23]
	v_pk_mul_f32 v[58:59], v[58:59], v[66:67]
	v_or_b32_e32 v66, 14, v40
	v_lshl_add_u32 v40, v66, 11, 0
	v_cvt_pk_bf16_f32 v53, v58, v59
	v_add3_u32 v40, v40, v80, v41
	ds_write2st64_b64 v40, v[52:53], v[44:45] offset1:2
	v_pk_mul_f32 v[44:45], v[60:61], v[18:19] op_sel:[1,0]
	v_pk_mul_f32 v[58:59], v[60:61], v[16:17] op_sel:[1,0]
	v_ashrrev_i32_e32 v67, 31, v66
	v_pk_fma_f32 v[44:45], v[46:47], v[14:15], v[44:45] op_sel_hi:[0,1,1]
	v_pk_fma_f32 v[58:59], v[46:47], v[12:13], v[58:59] op_sel_hi:[0,1,1]
	v_lshl_add_u64 v[60:61], s[16:17], 0, v[66:67]
	v_pk_fma_f32 v[44:45], v[62:63], v[10:11], v[44:45] op_sel_hi:[0,1,1]
	v_pk_fma_f32 v[58:59], v[62:63], v[8:9], v[58:59] op_sel_hi:[0,1,1]
	v_lshlrev_b64 v[60:61], 10, v[60:61]
	v_pk_fma_f32 v[44:45], v[64:65], v[6:7], v[44:45] op_sel:[1,0,0]
	v_pk_fma_f32 v[58:59], v[64:65], v[4:5], v[58:59] op_sel:[1,0,0]
	v_lshl_add_u64 v[64:65], s[50:51], 0, v[60:61]
	v_lshl_add_u64 v[64:65], v[64:65], 0, v[2:3]
	global_store_dwordx2 v[64:65], v[52:53], off
; #define GAS __attribute__((address_space(1)))
; #define LAS __attribute__((address_space(3)))
; #define MFMA16(a, b, c) __builtin_amdgcn_mfma_f32_16x16x32_bf16((a), (b), (c), 0, 0, 0)
; __device__ __forceinline__ float fsigmoid(float x) { return __builtin_amdgcn_rcpf(1.f + __builtin_amdgcn_exp2f(-LOG2E * x)); }
; __device__ __forceinline__ f32x4 bf4_to_f32(u32x2 w) { return (f32x4){bflo(w.x), bfhi(w.x), bflo(w.y), bfhi(w.y)}; }
; __device__ __forceinline__ u32x2 f32_to_bf4(f32x4 v) { u32x2 w; w.x = cvtpk(v[0], v[1]); w.y = cvtpk(v[2], v[3]); return w; }
; __device__ __forceinline__ void prep_unit(LAS unsigned char* lds, const MixBufs& B, int b, int ch, int tid) {
;     ...
;         for (int s = 0; s < 16; ++s) { const int row = 16 * strip + s;
;             const f32x4 x0 = bf4_to_f32(xr[s + 3]);
;             f32x4 cv = cb + cw[0] * x3 + cw[1] * x2 + cw[2] * x1 + cw[3] * x0, xc;
; #pragma unroll
;             for (int e = 0; e < 4; ++e) xc[e] = cv[e] * fsigmoid(cv[e]);
;             const int sw = row & 7, within = (gch & 1) * 8;
;             *(LAS u32x2*)(XA + row * 2048 + ((((gch >> 1)) ^ sw) << 4) + within) = f32_to_bf4(xc);
;             *(LAS u32x2*)(XA + row * 2048 + (((64 + (gch >> 1)) ^ sw) << 4) + within) = xr[s + 3];
;             const f32x4 v = wv[0] * x0[0] + wv[1] * x0[1] + wv[2] * x0[2] + wv[3] * x0[3];
;             *(GAS u32x2*)(B.xcm + (t0 + row) * 512 + 4 * gch) = f32_to_bf4(xc); *(GAS u32x2*)(B.vm + (t0 + row) * 512 + 4 * gch) = f32_to_bf4(v);
;             x3 = x2; x2 = x1; x1 = x0; }
;     }
;     __syncthreads();
;     LAS float* GP = (LAS float*)lds;
;     LAS float* GATES = (LAS float*)(lds + 32768);
;     {
;         f32x4 acc[4];
; #pragma unroll
;         for (int mt = 0; mt < 4; ++mt) acc[mt] = (f32x4){0.f, 0.f, 0.f, 0.f};
; #pragma unroll
;         for (int i = 0; i < 4; ++i) { const int ks = 4 * w + i;
;             const bf16x8 bw = *(const GAS bf16x8*)(B.WcmT + (size_t)(lane & 15) * 1024 + ks * 32 + 8 * (lane >> 4));
; #pragma unroll
;             for (int mt = 0; mt < 4; ++mt) { const int row = 16 * mt + (lane & 15);
;                 const bf16x8 a = *(const LAS bf16x8*)(XA + row * 2048 + (((4 * ks + (lane >> 4)) ^ (row & 7)) << 4)); acc[mt] = MFMA16(a, bw, acc[mt]); } }
	v_cvt_pk_bf16_f32 v53, v44, v45
	v_lshl_add_u64 v[44:45], s[0:1], 0, v[60:61]
	v_cvt_pk_bf16_f32 v52, v58, v59
	v_lshl_add_u64 v[44:45], v[44:45], 0, v[2:3]
	global_store_dwordx2 v[44:45], v[52:53], off
	v_and_b32_e32 v53, 0xffff0000, v42
	v_lshlrev_b32_e32 v44, 16, v42
	v_mov_b32_e32 v45, v53
	v_pk_fma_f32 v[20:21], v[32:33], v[44:45], v[20:21]
	v_and_b32_e32 v52, 16, v42
	v_mul_f32_e32 v24, 0xbfb8aa3b, v20
	v_mul_f32_e32 v25, 0xbfb8aa3b, v21
	v_exp_f32_e32 v24, v24
	v_exp_f32_e32 v25, v25
	v_pk_mul_f32 v[16:17], v[52:53], v[16:17] op_sel:[1,0]
	v_pk_mul_f32 v[18:19], v[52:53], v[18:19] op_sel:[1,0]
	v_add_f32_e32 v24, 1.0, v24
	v_add_f32_e32 v25, 1.0, v25
	v_rcp_f32_e32 v24, v24
	v_rcp_f32_e32 v25, v25
	v_pk_fma_f32 v[12:13], v[44:45], v[12:13], v[16:17] op_sel_hi:[0,1,1]
	v_and_b32_e32 v28, 16, v43
	v_pk_fma_f32 v[14:15], v[44:45], v[14:15], v[18:19] op_sel_hi:[0,1,1]
	v_pk_mul_f32 v[20:21], v[20:21], v[24:25]
	v_lshlrev_b32_e32 v24, 16, v43
	v_mov_b32_e32 v25, v29
	v_pk_fma_f32 v[22:23], v[34:35], v[24:25], v[22:23]
	v_cvt_pk_bf16_f32 v20, v20, v21
	v_mul_f32_e32 v25, 0xbfb8aa3b, v22
	v_exp_f32_e32 v25, v25
	v_lshrrev_b32_e32 v30, 4, v97
	v_and_b32_e32 v31, 7, v99
	v_add_f32_e32 v25, 1.0, v25
	v_rcp_f32_e32 v26, v25
	v_mul_f32_e32 v25, 0xbfb8aa3b, v23
	v_exp_f32_e32 v25, v25
	s_nop 0
	v_add_f32_e32 v25, 1.0, v25
	v_rcp_f32_e32 v27, v25
	v_pk_fma_f32 v[8:9], v[24:25], v[8:9], v[12:13] op_sel_hi:[0,1,1]
	v_pk_fma_f32 v[10:11], v[24:25], v[10:11], v[14:15] op_sel_hi:[0,1,1]
	v_pk_fma_f32 v[4:5], v[28:29], v[4:5], v[8:9] op_sel:[1,0,0]
	v_pk_mul_f32 v[22:23], v[22:23], v[26:27]
	v_or_b32_e32 v26, 15, v79
	v_ashrrev_i32_e32 v27, 31, v26
	v_lshl_add_u64 v[8:9], s[16:17], 0, v[26:27]
	v_pk_fma_f32 v[6:7], v[28:29], v[6:7], v[10:11] op_sel:[1,0,0]
	v_lshlrev_b64 v[8:9], 10, v[8:9]
	v_lshl_add_u64 v[10:11], s[50:51], 0, v[8:9]
	v_cvt_pk_bf16_f32 v4, v4, v5
	v_cvt_pk_bf16_f32 v5, v6, v7
	v_lshl_add_u64 v[6:7], s[0:1], 0, v[8:9]
	v_lshl_add_u64 v[10:11], v[10:11], 0, v[2:3]
	v_lshl_add_u64 v[6:7], v[6:7], 0, v[2:3]
	v_lshlrev_b32_e32 v2, 11, v100
	global_store_dwordx2 v[6:7], v[4:5], off
	v_lshl_add_u64 v[4:5], s[8:9], 0, v[2:3]
	v_and_b32_e32 v6, 48, v97
	v_mov_b32_e32 v7, v3
	v_cvt_pk_bf16_f32 v21, v22, v23
	v_lshl_add_u32 v22, v26, 11, 0
	v_lshl_add_u64 v[4:5], v[4:5], 0, v[6:7]
	v_add3_u32 v22, v22, v72, v41
	v_lshl_add_u64 v[6:7], s[4:5], 1, v[4:5]
	global_load_dwordx4 v[128:131], v[6:7], off offset:64
	global_load_dwordx4 v[132:135], v[6:7], off offset:128
	global_load_dwordx4 v[136:139], v[6:7], off offset:192
	v_lshlrev_b32_e32 v141, 2, v31
	global_load_dword v140, v141, s[76:77]
	ds_write2st64_b64 v22, v[20:21], v[42:43] offset1:2
	global_store_dwordx2 v[10:11], v[20:21], off
	s_waitcnt lgkmcnt(0)
	s_barrier
	global_load_dwordx4 v[6:9], v[6:7], off
	v_bitop3_b32 v10, s3, v31, v30 bitop3:0x36
	s_or_b32 s3, s2, 1
	v_add_u32_e32 v2, 0, v2
	s_lshl_b32 s4, s3, 5
	s_lshl_b32 s3, s3, 2
	v_lshl_add_u32 v22, v10, 4, v2
	v_bitop3_b32 v26, s3, v31, v30 bitop3:0x36
	v_add_u32_e32 v18, 0x10000, v22
	v_lshl_add_u32 v32, v26, 4, v2
	ds_read_b128 v[10:13], v22
	ds_read_b128 v[26:29], v32
	ds_read_b128 v[14:17], v22 offset:32768
	ds_read_b128 v[18:21], v18
	v_add_u32_e32 v22, 0x18000, v22
	ds_read_b128 v[22:25], v22
	s_ashr_i32 s5, s4, 31
	s_waitcnt vmcnt(0) lgkmcnt(4)
	v_mfma_f32_16x16x32_bf16 v[10:13], v[10:13], v[6:9], 0
	s_or_b32 s3, s2, 2
	s_waitcnt lgkmcnt(2)
	v_mfma_f32_16x16x32_bf16 v[14:17], v[14:17], v[6:9], 0
	s_waitcnt lgkmcnt(1)
	v_mfma_f32_16x16x32_bf16 v[18:21], v[18:21], v[6:9], 0
	s_waitcnt lgkmcnt(0)
	v_mfma_f32_16x16x32_bf16 v[6:9], v[22:25], v[6:9], 0
	v_lshl_add_u64 v[22:23], s[4:5], 1, v[4:5]
	s_nop 0
	s_lshl_b32 s4, s3, 5
	s_waitcnt vmcnt(0)
	v_mfma_f32_16x16x32_bf16 v[10:13], v[26:29], v[128:131], v[10:13]
	ds_read_b128 v[26:29], v32 offset:32768
	s_ashr_i32 s5, s4, 31
	s_lshl_b32 s3, s3, 2
	s_waitcnt lgkmcnt(0)
	v_mfma_f32_16x16x32_bf16 v[14:17], v[26:29], v[128:131], v[14:17]
	v_add_u32_e32 v26, 0x10000, v32
	ds_read_b128 v[26:29], v26
	s_waitcnt lgkmcnt(0)
	v_mfma_f32_16x16x32_bf16 v[18:21], v[26:29], v[128:131], v[18:21]
	v_add_u32_e32 v26, 0x18000, v32
	ds_read_b128 v[26:29], v26
	s_waitcnt lgkmcnt(0)
	v_mfma_f32_16x16x32_bf16 v[6:9], v[26:29], v[128:131], v[6:9]
	v_lshl_add_u64 v[22:23], s[4:5], 1, v[4:5]
	s_nop 0
	v_bitop3_b32 v26, s3, v31, v30 bitop3:0x36
	v_lshl_add_u32 v32, v26, 4, v2
	ds_read_b128 v[26:29], v32
	s_waitcnt vmcnt(0) lgkmcnt(0)
	v_mfma_f32_16x16x32_bf16 v[10:13], v[26:29], v[132:135], v[10:13]
	ds_read_b128 v[26:29], v32 offset:32768
	s_or_b32 s3, s2, 3
	s_lshl_b32 s4, s3, 5
	s_waitcnt lgkmcnt(0)
	v_mfma_f32_16x16x32_bf16 v[14:17], v[26:29], v[132:135], v[14:17]
	v_add_u32_e32 v26, 0x10000, v32
	ds_read_b128 v[26:29], v26
	s_ashr_i32 s5, s4, 31
	s_waitcnt lgkmcnt(0)
	v_mfma_f32_16x16x32_bf16 v[18:21], v[26:29], v[132:135], v[18:21]
	v_add_u32_e32 v26, 0x18000, v32
	ds_read_b128 v[26:29], v26
	v_lshl_add_u64 v[4:5], s[4:5], 1, v[4:5]
	s_waitcnt lgkmcnt(0)
	v_mfma_f32_16x16x32_bf16 v[6:9], v[26:29], v[132:135], v[6:9]
	s_nop 0
	s_lshl_b32 s3, s3, 2
	v_bitop3_b32 v4, s3, v31, v30 bitop3:0x36
	v_lshl_add_u32 v2, v4, 4, v2
	ds_read_b128 v[26:29], v2
	s_waitcnt vmcnt(0) lgkmcnt(0)
	v_mfma_f32_16x16x32_bf16 v[10:13], v[26:29], v[136:139], v[10:13]
	ds_read_b128 v[26:29], v2 offset:32768
	v_add_u32_e32 v4, 0x10000, v2
	v_add_u32_e32 v2, 0x18000, v2
	s_waitcnt lgkmcnt(0)
	v_mfma_f32_16x16x32_bf16 v[14:17], v[26:29], v[136:139], v[14:17]
	ds_read_b128 v[26:29], v4
	s_lshl_b32 s3, s18, 12
	s_add_i32 s3, s3, 0
	s_waitcnt lgkmcnt(0)
	v_mfma_f32_16x16x32_bf16 v[18:21], v[26:29], v[136:139], v[18:21]
	ds_read_b128 v[26:29], v2
	v_add_u32_e32 v2, s3, v78
	s_waitcnt lgkmcnt(0)
	v_mfma_f32_16x16x32_bf16 v[4:7], v[26:29], v[136:139], v[6:9]
	s_barrier
; #define LAS __attribute__((address_space(3)))
; __device__ __forceinline__ float fexp(float x) { return __builtin_amdgcn_exp2f(x * LOG2E); }
; __device__ __forceinline__ float flogsig(float x) { return fminf(x, 0.f) - __logf(1.f + fexp(-fabsf(x))); }
; __device__ __forceinline__ void prep_unit(LAS unsigned char* lds, const MixBufs& B, int b, int ch, int tid) {
;     ...
;         __syncthreads();
; #pragma unroll
;         for (int mt = 0; mt < 4; ++mt) *(LAS f32x4*)(GP + ((w * 4 + mt) * 64 + lane) * 4) = acc[mt];
;     }
;     __syncthreads();
;     { const int t = tid >> 3, jg = tid & 7, mt = t >> 4, tl = t & 15, ls = jg + 16 * (tl >> 2), rg = tl & 3;
;       float s = B.b_if[jg];
; #pragma unroll
;       for (int ww = 0; ww < 8; ++ww) s += GP[((ww * 4 + mt) * 64 + ls) * 4 + rg];
;       GATES[t * 8 + jg] = s; }
;     __syncthreads();
;     if (w < 4) {
;         const int h = w;
;         const float liv = GATES[lane * 8 + h], lfv = flogsig(GATES[lane * 8 + 4 + h]);
;         float fc = lfv;
; #pragma unroll
;         for (int o = 1; o < 64; o <<= 1) { const float u = __shfl_up(fc, o); if (lane >= o) fc += u; }
;         const float fl = __shfl(fc, 63);
;         const float a = fl - fc + liv;
;         float mx = a;
; #pragma unroll
;         for (int o = 1; o < 64; o <<= 1) mx = fmaxf(mx, __shfl_xor(mx, o));
;         B.li[(t0 + lane) * 4 + h] = liv; B.fcum[(t0 + lane) * 4 + h] = fc; B.wgt[(t0 + lane) * 4 + h] = fexp(a - mx);
;         if (lane == 0) { B.flast[((size_t)b * NCH + ch) * 4 + h] = fl; B.mloc[((size_t)b * NCH + ch) * 4 + h] = mx; }
;     }
	ds_write_b128 v2, v[10:13]
	ds_write_b128 v2, v[14:17] offset:1024
	s_nop 0
	ds_write_b128 v2, v[18:21] offset:2048
	s_nop 2
	ds_write_b128 v2, v[4:7] offset:3072
	v_lshlrev_b32_e32 v4, 2, v31
	s_waitcnt lgkmcnt(0)
	s_barrier
	s_nop 0
	v_lshlrev_b32_e32 v2, 2, v79
	v_lshrrev_b32_e32 v4, 1, v99
	v_and_b32_e32 v2, 48, v2
	v_and_b32_e32 v5, 0xfffffc0, v4
	v_or3_b32 v2, v5, v2, v31
	v_and_b32_e32 v4, 12, v4
	v_lshlrev_b32_e32 v2, 4, v2
	v_add3_u32 v2, 0, v4, v2
	ds_read2st64_b32 v[4:5], v2 offset1:16
	s_cmp_gt_i32 s18, 3
	s_waitcnt vmcnt(0) lgkmcnt(0)
	v_add_f32_e32 v4, v140, v4
	v_add_f32_e32 v6, v4, v5
	ds_read2st64_b32 v[4:5], v2 offset0:32 offset1:48
	s_waitcnt lgkmcnt(0)
	v_add_f32_e32 v4, v6, v4
	v_add_f32_e32 v6, v4, v5
	ds_read2st64_b32 v[4:5], v2 offset0:64 offset1:80
	s_waitcnt lgkmcnt(0)
	v_add_f32_e32 v4, v6, v4
	v_add_f32_e32 v6, v4, v5
	ds_read2st64_b32 v[4:5], v2 offset0:96 offset1:112
	s_waitcnt lgkmcnt(0)
	v_add_f32_e32 v2, v6, v4
	v_add_f32_e32 v2, v2, v5
	ds_write_b32 v98, v2 offset:32768
	s_waitcnt lgkmcnt(0)
	s_barrier
	s_cbranch_scc1 .LBB0_292
	s_add_i32 s2, s2, 0
	v_lshl_add_u32 v2, v97, 5, s2
	v_add_u32_e32 v2, 0x8000, v2
	ds_read2_b32 v[4:5], v2 offset1:4
	v_xor_b32_e32 v7, 2, v95
	s_ashr_i32 s19, s18, 31
	s_waitcnt lgkmcnt(0)
	v_max_f32_e32 v2, v5, v5
	v_mul_f32_e64 v5, |v5|, s22
	v_exp_f32_e32 v5, v5
	v_min_f32_e32 v2, 0, v2
	v_add_f32_e32 v5, 1.0, v5
	v_cmp_gt_f32_e32 vcc, s23, v5
	s_nop 1
	v_cndmask_b32_e64 v6, 0, 32, vcc
	v_ldexp_f32 v5, v5, v6
	v_log_f32_e32 v5, v5
	s_nop 0
	v_mul_f32_e32 v6, 0x3f317217, v5
	v_fma_f32 v6, v5, s24, -v6
	v_fmac_f32_e32 v6, 0x3377d1cf, v5
	v_fmac_f32_e32 v6, 0x3f317217, v5
	v_cmp_lt_f32_e64 s[2:3], |v5|, s25
	s_nop 1
	v_cndmask_b32_e64 v5, v5, v6, s[2:3]
	v_cndmask_b32_e32 v6, 0, v1, vcc
	v_sub_f32_e32 v5, v5, v6
	v_sub_f32_e32 v2, v2, v5
	v_and_b32_e32 v5, 64, v95
	v_add_u32_e32 v6, -1, v95
	v_cmp_lt_i32_e32 vcc, v6, v5
	s_nop 1
	v_cndmask_b32_e32 v6, v6, v95, vcc
	v_lshlrev_b32_e32 v6, 2, v6
	ds_bpermute_b32 v6, v6, v2
	v_cmp_eq_u32_e32 vcc, 0, v97
	s_waitcnt lgkmcnt(0)
	v_add_f32_e32 v6, v2, v6
	v_cndmask_b32_e32 v2, v6, v2, vcc
	v_add_u32_e32 v6, -2, v95
	v_cmp_lt_i32_e64 s[2:3], v6, v5
	s_nop 1
	v_cndmask_b32_e64 v6, v6, v95, s[2:3]
	v_lshlrev_b32_e32 v6, 2, v6
	ds_bpermute_b32 v6, v6, v2
	v_cmp_gt_u32_e64 s[2:3], 2, v97
	s_waitcnt lgkmcnt(0)
	v_add_f32_e32 v6, v2, v6
	v_cndmask_b32_e64 v2, v6, v2, s[2:3]
	v_add_u32_e32 v6, -4, v95
	v_cmp_lt_i32_e64 s[2:3], v6, v5
	s_nop 1
	v_cndmask_b32_e64 v6, v6, v95, s[2:3]
	v_lshlrev_b32_e32 v6, 2, v6
	ds_bpermute_b32 v6, v6, v2
	v_cmp_gt_u32_e64 s[2:3], 4, v97
	s_waitcnt lgkmcnt(0)
	v_add_f32_e32 v6, v2, v6
	v_cndmask_b32_e64 v2, v6, v2, s[2:3]
	v_add_u32_e32 v6, -8, v95
	v_cmp_lt_i32_e64 s[2:3], v6, v5
	s_nop 1
	v_cndmask_b32_e64 v6, v6, v95, s[2:3]
	v_lshlrev_b32_e32 v6, 2, v6
	ds_bpermute_b32 v6, v6, v2
	v_cmp_gt_u32_e64 s[2:3], 8, v97
	s_waitcnt lgkmcnt(0)
	v_add_f32_e32 v6, v2, v6
	v_cndmask_b32_e64 v2, v6, v2, s[2:3]
	v_add_u32_e32 v6, -16, v95
	v_cmp_lt_i32_e64 s[2:3], v6, v5
	s_nop 1
	v_cndmask_b32_e64 v6, v6, v95, s[2:3]
	v_lshlrev_b32_e32 v6, 2, v6
	ds_bpermute_b32 v6, v6, v2
	v_cmp_gt_u32_e64 s[2:3], 16, v97
	s_waitcnt lgkmcnt(0)
	v_add_f32_e32 v6, v2, v6
	v_cndmask_b32_e64 v2, v6, v2, s[2:3]
	v_subrev_u32_e32 v6, 32, v95
	v_cmp_lt_i32_e64 s[2:3], v6, v5
	v_add_u32_e32 v5, 64, v5
	s_nop 0
	v_cndmask_b32_e64 v6, v6, v95, s[2:3]
	v_lshlrev_b32_e32 v6, 2, v6
	ds_bpermute_b32 v6, v6, v2
	v_cmp_gt_u32_e64 s[2:3], 32, v97
	s_waitcnt lgkmcnt(0)
	v_add_f32_e32 v6, v2, v6
	v_cndmask_b32_e64 v10, v6, v2, s[2:3]
	ds_bpermute_b32 v2, v96, v10
	s_waitcnt lgkmcnt(0)
	v_sub_f32_e32 v6, v2, v10
	v_add_f32_e32 v11, v4, v6
	v_xor_b32_e32 v6, 1, v95
	v_cmp_lt_i32_e64 s[2:3], v6, v5
	s_nop 1
	v_cndmask_b32_e64 v6, v95, v6, s[2:3]
	v_lshlrev_b32_e32 v6, 2, v6
	ds_bpermute_b32 v6, v6, v11
	v_cmp_lt_i32_e64 s[2:3], v7, v5
	s_waitcnt lgkmcnt(0)
	v_max_f32_e32 v6, v6, v6
	v_cndmask_b32_e64 v7, v95, v7, s[2:3]
	v_max_f32_e32 v6, v11, v6
	v_lshlrev_b32_e32 v7, 2, v7
	ds_bpermute_b32 v7, v7, v6
	s_waitcnt lgkmcnt(0)
	v_max_f32_e32 v7, v7, v7
	v_max_f32_e32 v6, v6, v7
	v_xor_b32_e32 v7, 4, v95
	v_cmp_lt_i32_e64 s[2:3], v7, v5
	s_nop 1
	v_cndmask_b32_e64 v7, v95, v7, s[2:3]
	v_lshlrev_b32_e32 v7, 2, v7
	ds_bpermute_b32 v7, v7, v6
	s_waitcnt lgkmcnt(0)
	v_max_f32_e32 v7, v7, v7
	v_max_f32_e32 v6, v6, v7
	v_xor_b32_e32 v7, 8, v95
	v_cmp_lt_i32_e64 s[2:3], v7, v5
	s_nop 1
	v_cndmask_b32_e64 v7, v95, v7, s[2:3]
	v_lshlrev_b32_e32 v7, 2, v7
	ds_bpermute_b32 v7, v7, v6
	s_waitcnt lgkmcnt(0)
	v_max_f32_e32 v7, v7, v7
	v_max_f32_e32 v6, v6, v7
	v_xor_b32_e32 v7, 16, v95
	v_cmp_lt_i32_e64 s[2:3], v7, v5
	s_nop 1
	v_cndmask_b32_e64 v7, v95, v7, s[2:3]
	v_lshlrev_b32_e32 v7, 2, v7
	ds_bpermute_b32 v7, v7, v6
	s_waitcnt lgkmcnt(0)
	v_max_f32_e32 v7, v7, v7
	v_max_f32_e32 v6, v6, v7
	v_xor_b32_e32 v7, 32, v95
	v_cmp_lt_i32_e64 s[2:3], v7, v5
	s_nop 1
	v_cndmask_b32_e64 v5, v95, v7, s[2:3]
	v_lshlrev_b32_e32 v5, 2, v5
	ds_bpermute_b32 v5, v5, v6
	v_mov_b32_e32 v7, s17
	v_readlane_b32 s2, v241, 59
	v_readlane_b32 s3, v241, 60
	s_waitcnt lgkmcnt(0)
	v_max_f32_e32 v5, v5, v5
	v_max_f32_e32 v5, v6, v5
	v_or_b32_e32 v6, s16, v97
	v_lshl_add_u64 v[6:7], v[6:7], 2, s[18:19]
	v_lshlrev_b64 v[6:7], 2, v[6:7]
	v_lshl_add_u64 v[8:9], s[2:3], 0, v[6:7]
	global_store_dword v[8:9], v4, off
	v_sub_f32_e32 v4, v11, v5
	v_readlane_b32 s2, v241, 61
	v_mul_f32_e32 v4, 0x3fb8aa3b, v4
	v_readlane_b32 s3, v241, 62
	v_exp_f32_e32 v4, v4
	s_nop 0
	v_lshl_add_u64 v[8:9], s[2:3], 0, v[6:7]
	v_readlane_b32 s2, v241, 63
	v_readlane_b32 s3, v240, 0
	global_store_dword v[8:9], v10, off
	s_nop 0
	v_lshl_add_u64 v[6:7], s[2:3], 0, v[6:7]
	global_store_dword v[6:7], v4, off
	s_and_saveexec_b64 s[2:3], vcc
	s_cbranch_execz .LBB0_291
	s_lshl_b64 s[4:5], s[14:15], 7
	s_lshl_b32 s6, s27, 2
	s_or_b32 s4, s4, s6
	s_add_u32 s4, s4, s18
	s_addc_u32 s5, s5, s19
	s_lshl_b64 s[4:5], s[4:5], 2
	v_readlane_b32 s6, v240, 1
	v_readlane_b32 s7, v240, 2
	s_add_u32 s6, s6, s4
	s_addc_u32 s7, s7, s5
	s_nop 2
	global_store_dword v3, v2, s[6:7]
	v_readlane_b32 s6, v240, 3
	v_readlane_b32 s7, v240, 4
	s_add_u32 s4, s6, s4
	s_addc_u32 s5, s7, s5
	global_store_dword v3, v5, s[4:5]
	s_branch .LBB0_291

; __device__ __forceinline__ void p0_transposes(Frame& F, int it_lo, int it_hi, int gw, int NGW) {
;     ...
;     int it = it_lo + gw; if (it >= it_hi) return;
;     TrItem cur = tr_decode(F, it); f32x4 v[8]; float g[8];
;     tr_load(cur, v, g, lane);
;     for (;;) {
;         const int nx = it + NGW; const bool more = nx < it_hi;
; template <int PH> __device__ __forceinline__ void run_phase(Frame& F, const Args& args) {
;     ...
;             if (F.G == 256 && ((F.vcu >> 4) & 1) == 0) { __syncthreads(); p0_transposes(F, P0_I_W1 + P0_SPLIT, P0_NITEMS, (((F.vcu >> 5) << 4) | (F.vcu & 15)) * NWAVES + F.wave, 128 * NWAVES); }
.LBB0_870:
	v_readlane_b32 s2, v241, 52
	s_bitcmp0_b32 s2, 4
	s_movk_i32 s101, 0x1980
	s_cselect_b32 s100, 0, 0x1000
	s_cselect_b32 s101, 0x1580, s101
	v_readlane_b32 s4, v241, 46
	s_mov_b64 s[0:1], -1
	v_readlane_b32 s5, v241, 47
	s_and_b64 s[0:1], s[4:5], s[0:1]
	v_readlane_b32 s68, v241, 42
	v_readlane_b32 s74, v240, 9
	s_and_b64 vcc, exec, s[0:1]
	v_readlane_b32 s66, v240, 13
	v_readlane_b32 s69, v241, 43
	v_readlane_b32 s70, v241, 50
	v_readlane_b32 s72, v240, 11
	v_readlane_b32 s75, v240, 10
	v_readlane_b32 s67, v240, 8
	v_readlane_b32 s76, v240, 7
	v_readlane_b32 s71, v241, 51
	v_readlane_b32 s73, v240, 12
	s_cbranch_vccz .LBB0_1025
	s_lshr_b32 s0, s2, 1
	s_and_b32 s0, s0, 0x1ffffff0
	s_and_b32 s1, s2, 15
	s_or_b32 s0, s0, s1
	s_lshl_b32 s12, s0, 3
	v_readlane_b32 s0, v241, 48
	s_add_i32 s12, s12, s0
	v_mov_b32_e32 v1, v0
	s_add_i32 s12, s12, s100
	s_cmpk_gt_i32 s12, 0x13ff
	s_barrier
	s_cbranch_scc1 .LBB0_1025
	s_add_i32 s22, s12, 0x980
	s_cmp_gt_i32 s12, -1
	s_cbranch_scc0 .LBB0_878
	s_cmpk_gt_u32 s22, 0xa7f
	s_cbranch_scc0 .LBB0_880
	s_cmpk_gt_u32 s22, 0xb7f
	s_cbranch_scc0 .LBB0_932
	s_cmpk_gt_u32 s22, 0xd7f
	s_cbranch_scc0 .LBB0_933
	s_lshl_b32 s4, s22, 5
	s_cmpk_gt_u32 s22, 0x157f
	s_cbranch_scc0 .LBB0_934
	v_readlane_b32 s36, v241, 18
	s_add_i32 s0, s12, 0xfffff400
	v_readlane_b32 s46, v241, 28
	v_readlane_b32 s47, v241, 29
	s_lshr_b32 s23, s0, 5
	s_and_b32 s24, s4, 0x3e0
	s_mov_b64 s[0:1], 0
	s_mov_b64 s[2:3], 0
	v_readlane_b32 s37, v241, 19
	v_readlane_b32 s38, v241, 20
	v_readlane_b32 s39, v241, 21
	v_readlane_b32 s40, v241, 22
	v_readlane_b32 s41, v241, 23
	v_readlane_b32 s42, v241, 24
	v_readlane_b32 s43, v241, 25
	v_readlane_b32 s44, v241, 26
	v_readlane_b32 s45, v241, 27
	v_readlane_b32 s48, v241, 30
	v_readlane_b32 s49, v241, 31
	v_readlane_b32 s50, v241, 32
	v_readlane_b32 s51, v241, 33
	s_mov_b64 s[6:7], s[46:47]
	s_branch .LBB0_935
